# silu(gate) applied in f32 in the attention in-proj GEMM epilogue of gate tiles (stored bf16 = silu(gate)), attention epilogue multiplies by it; plus hand-written attention phase
# baseline (speedup 1.0000x reference)
; __device__ __forceinline__ unsigned cvt_pk_bf16(float lo, float hi) { unsigned r; asm volatile("v_cvt_pk_bf16_f32 %0, %1, %2" : "=v"(r) : "v"(lo), "v"(hi)); return r; }
;     __device__ __forceinline__ void operator()(const f32x4 (&acc)[2][2][4][2], const Unit& u, int wr, int wc, int fr, int fq) const {
;         const int row0 = u.pm * BM + wr * 64 + fr, colt = u.pn * BM, region = colt >> 10;
;         const float sc = (region == 0) ? qscale : 1.f;
;         bf16_t* base = QF + (size_t)region * ((size_t)16384 * 1024);
; #pragma unroll
;         for (int ai = 0; ai < 2; ++ai)
; #pragma unroll
;             for (int m = 0; m < 4; ++m) { const int row = row0 + ai * HALF + m * 16;
;                 const float rs = __builtin_amdgcn_rsqf(ssq[row] * (1.0f / 1024.0f) + 1e-6f) * sc;
;                 const int b = row >> 12, tl = row & 4095, tile = tl >> 5, r = tl & 31;
; #pragma unroll
;                 for (int bj = 0; bj < 2; ++bj) { const int cc = (colt & 1023) + bj * HALF + wc * 32 + 8 * fq, h = cc >> 6, d8 = cc & 63, bh = b * 16 + h;
;                     const f32x4 v0 = acc[ai][bj][m][0] * rs, v1 = acc[ai][bj][m][1] * rs;
;                     u32x4 w; w.x = cvt_pk_bf16(v0[0], v0[1]); w.y = cvt_pk_bf16(v0[2], v0[3]); w.z = cvt_pk_bf16(v1[0], v1[1]); w.w = cvt_pk_bf16(v1[2], v1[3]);
;                     if (region < 2) { const int ks = d8 >> 4, hh = (d8 >> 3) & 1;
;                         *(u32x4*)(base + ((size_t)(((bh * 128 + tile) * 4 + ks) * 64 + hh * 32 + r) << 3)) = w;
;                     } else { const int dt = d8 >> 5, g = (d8 >> 3) & 3; bf16_t* p = base + ((size_t)((((bh * 128 + tile) * 2 + dt) * 4 + g) * 64 + r) << 2);
;                         *(unsigned long long*)p = (unsigned long long)w.x | ((unsigned long long)w.y << 32);
;                         *(unsigned long long*)(p + 128) = (unsigned long long)w.z | ((unsigned long long)w.w << 32); } }
.LBB0_493:
	s_lshl_b32 s5, s24, 8
	s_add_i32 s17, s5, s48
	v_or_b32_e32 v144, s17, v162
	v_ashrrev_i32_e32 v145, 31, v144
	v_lshl_add_u64 v[146:147], v[144:145], 2, s[8:9]
	global_load_dword v148, v[146:147], off
	s_lshl_b32 s19, s4, 8
	s_ashr_i32 s26, s4, 2
	s_cmp_lt_u32 s4, 4
	s_cselect_b64 vcc, -1, 0
	s_ashr_i32 s27, s26, 31
	s_lshl_b64 s[4:5], s[26:27], 25
	s_add_u32 s24, s46, s4
	s_addc_u32 s25, s47, s5
	s_and_b32 s4, s19, 0x300
	s_or_b32 s4, s4, s49
	s_cmp_gt_i32 s26, 1
	s_cselect_b64 s[26:27], -1, 0
	s_cselect_b32 s95, 1, 0
	s_lshr_b32 s19, s17, 5
	v_cndmask_b32_e32 v145, 1.0, v166, vcc
	s_ashr_i32 s5, s17, 8
	s_and_b32 s31, s19, 0x7e
	s_lshr_b32 s17, s4, 6
	s_and_b32 s4, s5, -16
	s_lshl_b32 s5, s31, 3
	s_mov_b64 s[28:29], -1
	s_and_b64 vcc, exec, s[26:27]
	s_or_b32 s30, s4, s17
	s_or_b32 s76, s5, s69
	s_waitcnt vmcnt(0)
	v_fmamk_f32 v148, v148, 0x3a800000, v165
	v_rsq_f32_e32 v148, v148
	s_nop 0
	v_mul_f32_e32 v148, v145, v148
	v_pk_mul_f32 v[168:169], v[122:123], v[148:149] op_sel_hi:[1,0]
	v_pk_mul_f32 v[122:123], v[120:121], v[148:149] op_sel_hi:[1,0]
	v_pk_mul_f32 v[126:127], v[126:127], v[148:149] op_sel_hi:[1,0]
	v_pk_mul_f32 v[124:125], v[124:125], v[148:149] op_sel_hi:[1,0]
	s_nop 0
	s_cmp_eq_u32 s95, 0
	s_cbranch_scc1 .Lsilu_skip_0
	v_mul_f32_e32 v200, 0xbfb8aa3b, v124
	v_mul_f32_e32 v201, 0xbfb8aa3b, v125
	v_mul_f32_e32 v202, 0xbfb8aa3b, v126
	v_mul_f32_e32 v203, 0xbfb8aa3b, v127
	v_mul_f32_e32 v204, 0xbfb8aa3b, v122
	v_mul_f32_e32 v205, 0xbfb8aa3b, v123
	v_mul_f32_e32 v206, 0xbfb8aa3b, v168
	v_mul_f32_e32 v207, 0xbfb8aa3b, v169
	v_exp_f32_e32 v200, v200
	v_exp_f32_e32 v201, v201
	v_exp_f32_e32 v202, v202
	v_exp_f32_e32 v203, v203
	v_exp_f32_e32 v204, v204
	v_exp_f32_e32 v205, v205
	v_exp_f32_e32 v206, v206
	v_exp_f32_e32 v207, v207
	v_add_f32_e32 v200, 1.0, v200
	v_add_f32_e32 v201, 1.0, v201
	v_add_f32_e32 v202, 1.0, v202
	v_add_f32_e32 v203, 1.0, v203
	v_add_f32_e32 v204, 1.0, v204
	v_add_f32_e32 v205, 1.0, v205
	v_add_f32_e32 v206, 1.0, v206
	v_add_f32_e32 v207, 1.0, v207
	v_rcp_f32_e32 v200, v200
	v_rcp_f32_e32 v201, v201
	v_rcp_f32_e32 v202, v202
	v_rcp_f32_e32 v203, v203
	v_rcp_f32_e32 v204, v204
	v_rcp_f32_e32 v205, v205
	v_rcp_f32_e32 v206, v206
	v_rcp_f32_e32 v207, v207
	v_mul_f32_e32 v124, v200, v124
	v_mul_f32_e32 v125, v201, v125
	v_mul_f32_e32 v126, v202, v126
	v_mul_f32_e32 v127, v203, v127
	v_mul_f32_e32 v122, v204, v122
	v_mul_f32_e32 v123, v205, v123
	v_mul_f32_e32 v168, v206, v168
	v_mul_f32_e32 v169, v207, v169
.Lsilu_skip_0:
	v_cvt_pk_bf16_f32 v120, v124, v125
	v_cvt_pk_bf16_f32 v121, v126, v127
	v_cvt_pk_bf16_f32 v122, v122, v123
	v_cvt_pk_bf16_f32 v123, v168, v169
	s_cbranch_vccz .LBB0_495
	s_lshl_b32 s5, s30, 10
	s_or_b32 s5, s76, s5
	v_or_b32_e32 v124, s5, v154
	v_lshl_or_b32 v124, v124, 6, v162
	v_ashrrev_i32_e32 v125, 31, v124
	v_lshl_add_u64 v[124:125], v[124:125], 3, s[24:25]
	global_store_dwordx2 v[124:125], v[120:121], off
	global_store_dwordx2 v[124:125], v[122:123], off offset:256
	s_mov_b64 s[28:29], 0

; __device__ __forceinline__ unsigned cvt_pk_bf16(float lo, float hi) { unsigned r; asm volatile("v_cvt_pk_bf16_f32 %0, %1, %2" : "=v"(r) : "v"(lo), "v"(hi)); return r; }
;     __device__ __forceinline__ void operator()(const f32x4 (&acc)[2][2][4][2], const Unit& u, int wr, int wc, int fr, int fq) const {
;     ...
;             for (int m = 0; m < 4; ++m) { const int row = row0 + ai * HALF + m * 16;
;                 const float rs = __builtin_amdgcn_rsqf(ssq[row] * (1.0f / 1024.0f) + 1e-6f) * sc;
;                 const int b = row >> 12, tl = row & 4095, tile = tl >> 5, r = tl & 31;
; #pragma unroll
;                 for (int bj = 0; bj < 2; ++bj) { const int cc = (colt & 1023) + bj * HALF + wc * 32 + 8 * fq, h = cc >> 6, d8 = cc & 63, bh = b * 16 + h;
;                     const f32x4 v0 = acc[ai][bj][m][0] * rs, v1 = acc[ai][bj][m][1] * rs;
;                     u32x4 w; w.x = cvt_pk_bf16(v0[0], v0[1]); w.y = cvt_pk_bf16(v0[2], v0[3]); w.z = cvt_pk_bf16(v1[0], v1[1]); w.w = cvt_pk_bf16(v1[2], v1[3]);
;                     if (region < 2) { const int ks = d8 >> 4, hh = (d8 >> 3) & 1;
;                         *(u32x4*)(base + ((size_t)(((bh * 128 + tile) * 4 + ks) * 64 + hh * 32 + r) << 3)) = w;
;                     } else { const int dt = d8 >> 5, g = (d8 >> 3) & 3; bf16_t* p = base + ((size_t)((((bh * 128 + tile) * 2 + dt) * 4 + g) * 64 + r) << 2);
;                         *(unsigned long long*)p = (unsigned long long)w.x | ((unsigned long long)w.y << 32);
;                         *(unsigned long long*)(p + 128) = (unsigned long long)w.z | ((unsigned long long)w.w << 32); } }
.LBB0_497:
	v_mov_b32_e32 v149, v148
	s_nop 0
	v_mov_b32_e32 v120, v148
	v_mov_b32_e32 v121, v148
	v_pk_mul_f32 v[116:117], v[116:117], v[148:149]
	s_or_b32 s19, s17, 2
	v_pk_mul_f32 v[118:119], v[118:119], v[120:121]
	v_pk_mul_f32 v[120:121], v[114:115], v[120:121]
	v_pk_mul_f32 v[114:115], v[112:113], v[148:149]
	s_cmp_eq_u32 s95, 0
	s_cbranch_scc1 .Lsilu_skip_1
	v_mul_f32_e32 v200, 0xbfb8aa3b, v116
	v_mul_f32_e32 v201, 0xbfb8aa3b, v117
	v_mul_f32_e32 v202, 0xbfb8aa3b, v118
	v_mul_f32_e32 v203, 0xbfb8aa3b, v119
	v_mul_f32_e32 v204, 0xbfb8aa3b, v114
	v_mul_f32_e32 v205, 0xbfb8aa3b, v115
	v_mul_f32_e32 v206, 0xbfb8aa3b, v120
	v_mul_f32_e32 v207, 0xbfb8aa3b, v121
	v_exp_f32_e32 v200, v200
	v_exp_f32_e32 v201, v201
	v_exp_f32_e32 v202, v202
	v_exp_f32_e32 v203, v203
	v_exp_f32_e32 v204, v204
	v_exp_f32_e32 v205, v205
	v_exp_f32_e32 v206, v206
	v_exp_f32_e32 v207, v207
	v_add_f32_e32 v200, 1.0, v200
	v_add_f32_e32 v201, 1.0, v201
	v_add_f32_e32 v202, 1.0, v202
	v_add_f32_e32 v203, 1.0, v203
	v_add_f32_e32 v204, 1.0, v204
	v_add_f32_e32 v205, 1.0, v205
	v_add_f32_e32 v206, 1.0, v206
	v_add_f32_e32 v207, 1.0, v207
	v_rcp_f32_e32 v200, v200
	v_rcp_f32_e32 v201, v201
	v_rcp_f32_e32 v202, v202
	v_rcp_f32_e32 v203, v203
	v_rcp_f32_e32 v204, v204
	v_rcp_f32_e32 v205, v205
	v_rcp_f32_e32 v206, v206
	v_rcp_f32_e32 v207, v207
	v_mul_f32_e32 v116, v200, v116
	v_mul_f32_e32 v117, v201, v117
	v_mul_f32_e32 v118, v202, v118
	v_mul_f32_e32 v119, v203, v119
	v_mul_f32_e32 v114, v204, v114
	v_mul_f32_e32 v115, v205, v115
	v_mul_f32_e32 v120, v206, v120
	v_mul_f32_e32 v121, v207, v121
.Lsilu_skip_1:
	v_cvt_pk_bf16_f32 v112, v116, v117
	v_cndmask_b32_e64 v116, 0, 1, s[26:27]
	s_or_b32 s28, s19, s4
	v_cmp_ne_u32_e64 s[4:5], 1, v116
	s_andn2_b64 vcc, exec, s[26:27]
	s_mov_b64 s[26:27], -1
	v_cvt_pk_bf16_f32 v113, v118, v119
	v_cvt_pk_bf16_f32 v114, v114, v115
	v_cvt_pk_bf16_f32 v115, v120, v121
	s_cbranch_vccnz .LBB0_499
	s_lshl_b32 s26, s28, 10
	s_or_b32 s26, s76, s26
	v_or_b32_e32 v116, s26, v154
	v_lshl_or_b32 v116, v116, 6, v162
	v_ashrrev_i32_e32 v117, 31, v116
	v_lshl_add_u64 v[116:117], v[116:117], 3, s[24:25]
	s_mov_b64 s[26:27], 0
	global_store_dwordx2 v[116:117], v[112:113], off
	global_store_dwordx2 v[116:117], v[114:115], off offset:256

; __device__ __forceinline__ unsigned cvt_pk_bf16(float lo, float hi) { unsigned r; asm volatile("v_cvt_pk_bf16_f32 %0, %1, %2" : "=v"(r) : "v"(lo), "v"(hi)); return r; }
;     __device__ __forceinline__ void operator()(const f32x4 (&acc)[2][2][4][2], const Unit& u, int wr, int wc, int fr, int fq) const {
;     ...
;             for (int m = 0; m < 4; ++m) { const int row = row0 + ai * HALF + m * 16;
;                 const float rs = __builtin_amdgcn_rsqf(ssq[row] * (1.0f / 1024.0f) + 1e-6f) * sc;
;                 const int b = row >> 12, tl = row & 4095, tile = tl >> 5, r = tl & 31;
; #pragma unroll
;                 for (int bj = 0; bj < 2; ++bj) { const int cc = (colt & 1023) + bj * HALF + wc * 32 + 8 * fq, h = cc >> 6, d8 = cc & 63, bh = b * 16 + h;
;                     const f32x4 v0 = acc[ai][bj][m][0] * rs, v1 = acc[ai][bj][m][1] * rs;
;                     u32x4 w; w.x = cvt_pk_bf16(v0[0], v0[1]); w.y = cvt_pk_bf16(v0[2], v0[3]); w.z = cvt_pk_bf16(v1[0], v1[1]); w.w = cvt_pk_bf16(v1[2], v1[3]);
;                     if (region < 2) { const int ks = d8 >> 4, hh = (d8 >> 3) & 1;
;                         *(u32x4*)(base + ((size_t)(((bh * 128 + tile) * 4 + ks) * 64 + hh * 32 + r) << 3)) = w;
;                     } else { const int dt = d8 >> 5, g = (d8 >> 3) & 3; bf16_t* p = base + ((size_t)((((bh * 128 + tile) * 2 + dt) * 4 + g) * 64 + r) << 2);
;                         *(unsigned long long*)p = (unsigned long long)w.x | ((unsigned long long)w.y << 32);
;                         *(unsigned long long*)(p + 128) = (unsigned long long)w.z | ((unsigned long long)w.w << 32); } }
.LBB0_501:
	global_load_dword v112, v[146:147], off offset:64
	s_and_b64 vcc, exec, s[4:5]
	s_mov_b64 s[26:27], -1
	s_waitcnt vmcnt(0)
	v_fmamk_f32 v112, v112, 0x3a800000, v165
	v_rsq_f32_e32 v112, v112
	s_nop 0
	v_mul_f32_e32 v112, v145, v112
	v_pk_mul_f32 v[114:115], v[106:107], v[112:113] op_sel_hi:[1,0]
	v_pk_mul_f32 v[106:107], v[104:105], v[112:113] op_sel_hi:[1,0]
	v_pk_mul_f32 v[110:111], v[110:111], v[112:113] op_sel_hi:[1,0]
	v_pk_mul_f32 v[108:109], v[108:109], v[112:113] op_sel_hi:[1,0]
	s_nop 0
	s_cmp_eq_u32 s95, 0
	s_cbranch_scc1 .Lsilu_skip_2
	v_mul_f32_e32 v200, 0xbfb8aa3b, v108
	v_mul_f32_e32 v201, 0xbfb8aa3b, v109
	v_mul_f32_e32 v202, 0xbfb8aa3b, v110
	v_mul_f32_e32 v203, 0xbfb8aa3b, v111
	v_mul_f32_e32 v204, 0xbfb8aa3b, v106
	v_mul_f32_e32 v205, 0xbfb8aa3b, v107
	v_mul_f32_e32 v206, 0xbfb8aa3b, v114
	v_mul_f32_e32 v207, 0xbfb8aa3b, v115
	v_exp_f32_e32 v200, v200
	v_exp_f32_e32 v201, v201
	v_exp_f32_e32 v202, v202
	v_exp_f32_e32 v203, v203
	v_exp_f32_e32 v204, v204
	v_exp_f32_e32 v205, v205
	v_exp_f32_e32 v206, v206
	v_exp_f32_e32 v207, v207
	v_add_f32_e32 v200, 1.0, v200
	v_add_f32_e32 v201, 1.0, v201
	v_add_f32_e32 v202, 1.0, v202
	v_add_f32_e32 v203, 1.0, v203
	v_add_f32_e32 v204, 1.0, v204
	v_add_f32_e32 v205, 1.0, v205
	v_add_f32_e32 v206, 1.0, v206
	v_add_f32_e32 v207, 1.0, v207
	v_rcp_f32_e32 v200, v200
	v_rcp_f32_e32 v201, v201
	v_rcp_f32_e32 v202, v202
	v_rcp_f32_e32 v203, v203
	v_rcp_f32_e32 v204, v204
	v_rcp_f32_e32 v205, v205
	v_rcp_f32_e32 v206, v206
	v_rcp_f32_e32 v207, v207
	v_mul_f32_e32 v108, v200, v108
	v_mul_f32_e32 v109, v201, v109
	v_mul_f32_e32 v110, v202, v110
	v_mul_f32_e32 v111, v203, v111
	v_mul_f32_e32 v106, v204, v106
	v_mul_f32_e32 v107, v205, v107
	v_mul_f32_e32 v114, v206, v114
	v_mul_f32_e32 v115, v207, v115
.Lsilu_skip_2:
	v_cvt_pk_bf16_f32 v104, v108, v109
	v_cvt_pk_bf16_f32 v105, v110, v111
	v_cvt_pk_bf16_f32 v106, v106, v107
	v_cvt_pk_bf16_f32 v107, v114, v115
	s_cbranch_vccnz .LBB0_503
	s_lshl_b32 s26, s30, 10
	s_or_b32 s26, s76, s26
	v_or_b32_e32 v108, s26, v154
	v_lshl_or_b32 v108, v108, 6, v158
	v_ashrrev_i32_e32 v109, 31, v108
	v_lshl_add_u64 v[108:109], v[108:109], 3, s[24:25]
	s_mov_b64 s[26:27], 0
	global_store_dwordx2 v[108:109], v[104:105], off
	global_store_dwordx2 v[108:109], v[106:107], off offset:256

; __device__ __forceinline__ unsigned cvt_pk_bf16(float lo, float hi) { unsigned r; asm volatile("v_cvt_pk_bf16_f32 %0, %1, %2" : "=v"(r) : "v"(lo), "v"(hi)); return r; }
;     __device__ __forceinline__ void operator()(const f32x4 (&acc)[2][2][4][2], const Unit& u, int wr, int wc, int fr, int fq) const {
;     ...
;             for (int m = 0; m < 4; ++m) { const int row = row0 + ai * HALF + m * 16;
;                 const float rs = __builtin_amdgcn_rsqf(ssq[row] * (1.0f / 1024.0f) + 1e-6f) * sc;
;                 const int b = row >> 12, tl = row & 4095, tile = tl >> 5, r = tl & 31;
; #pragma unroll
;                 for (int bj = 0; bj < 2; ++bj) { const int cc = (colt & 1023) + bj * HALF + wc * 32 + 8 * fq, h = cc >> 6, d8 = cc & 63, bh = b * 16 + h;
;                     const f32x4 v0 = acc[ai][bj][m][0] * rs, v1 = acc[ai][bj][m][1] * rs;
;                     u32x4 w; w.x = cvt_pk_bf16(v0[0], v0[1]); w.y = cvt_pk_bf16(v0[2], v0[3]); w.z = cvt_pk_bf16(v1[0], v1[1]); w.w = cvt_pk_bf16(v1[2], v1[3]);
;                     if (region < 2) { const int ks = d8 >> 4, hh = (d8 >> 3) & 1;
;                         *(u32x4*)(base + ((size_t)(((bh * 128 + tile) * 4 + ks) * 64 + hh * 32 + r) << 3)) = w;
;                     } else { const int dt = d8 >> 5, g = (d8 >> 3) & 3; bf16_t* p = base + ((size_t)((((bh * 128 + tile) * 2 + dt) * 4 + g) * 64 + r) << 2);
;                         *(unsigned long long*)p = (unsigned long long)w.x | ((unsigned long long)w.y << 32);
;                         *(unsigned long long*)(p + 128) = (unsigned long long)w.z | ((unsigned long long)w.w << 32); } }
.LBB0_505:
	v_mov_b32_e32 v113, v112
	s_nop 0
	v_mov_b32_e32 v104, v112
	v_mov_b32_e32 v105, v112
	v_pk_mul_f32 v[102:103], v[102:103], v[104:105]
	v_pk_mul_f32 v[104:105], v[98:99], v[104:105]
	v_pk_mul_f32 v[98:99], v[96:97], v[112:113]
	s_and_b64 vcc, exec, s[4:5]
	s_mov_b64 s[26:27], -1
	v_pk_mul_f32 v[100:101], v[100:101], v[112:113]
	s_nop 0
	s_cmp_eq_u32 s95, 0
	s_cbranch_scc1 .Lsilu_skip_3
	v_mul_f32_e32 v200, 0xbfb8aa3b, v100
	v_mul_f32_e32 v201, 0xbfb8aa3b, v101
	v_mul_f32_e32 v202, 0xbfb8aa3b, v102
	v_mul_f32_e32 v203, 0xbfb8aa3b, v103
	v_mul_f32_e32 v204, 0xbfb8aa3b, v98
	v_mul_f32_e32 v205, 0xbfb8aa3b, v99
	v_mul_f32_e32 v206, 0xbfb8aa3b, v104
	v_mul_f32_e32 v207, 0xbfb8aa3b, v105
	v_exp_f32_e32 v200, v200
	v_exp_f32_e32 v201, v201
	v_exp_f32_e32 v202, v202
	v_exp_f32_e32 v203, v203
	v_exp_f32_e32 v204, v204
	v_exp_f32_e32 v205, v205
	v_exp_f32_e32 v206, v206
	v_exp_f32_e32 v207, v207
	v_add_f32_e32 v200, 1.0, v200
	v_add_f32_e32 v201, 1.0, v201
	v_add_f32_e32 v202, 1.0, v202
	v_add_f32_e32 v203, 1.0, v203
	v_add_f32_e32 v204, 1.0, v204
	v_add_f32_e32 v205, 1.0, v205
	v_add_f32_e32 v206, 1.0, v206
	v_add_f32_e32 v207, 1.0, v207
	v_rcp_f32_e32 v200, v200
	v_rcp_f32_e32 v201, v201
	v_rcp_f32_e32 v202, v202
	v_rcp_f32_e32 v203, v203
	v_rcp_f32_e32 v204, v204
	v_rcp_f32_e32 v205, v205
	v_rcp_f32_e32 v206, v206
	v_rcp_f32_e32 v207, v207
	v_mul_f32_e32 v100, v200, v100
	v_mul_f32_e32 v101, v201, v101
	v_mul_f32_e32 v102, v202, v102
	v_mul_f32_e32 v103, v203, v103
	v_mul_f32_e32 v98, v204, v98
	v_mul_f32_e32 v99, v205, v99
	v_mul_f32_e32 v104, v206, v104
	v_mul_f32_e32 v105, v207, v105
.Lsilu_skip_3:
	v_cvt_pk_bf16_f32 v96, v100, v101
	v_cvt_pk_bf16_f32 v97, v102, v103
	v_cvt_pk_bf16_f32 v98, v98, v99
	v_cvt_pk_bf16_f32 v99, v104, v105
	s_cbranch_vccnz .LBB0_507
	s_lshl_b32 s26, s28, 10
	s_or_b32 s26, s76, s26
	v_or_b32_e32 v100, s26, v154
	v_lshl_or_b32 v100, v100, 6, v158
	v_ashrrev_i32_e32 v101, 31, v100
	v_lshl_add_u64 v[100:101], v[100:101], 3, s[24:25]
	s_mov_b64 s[26:27], 0
	global_store_dwordx2 v[100:101], v[96:97], off
	global_store_dwordx2 v[100:101], v[98:99], off offset:256

; __device__ __forceinline__ unsigned cvt_pk_bf16(float lo, float hi) { unsigned r; asm volatile("v_cvt_pk_bf16_f32 %0, %1, %2" : "=v"(r) : "v"(lo), "v"(hi)); return r; }
;     __device__ __forceinline__ void operator()(const f32x4 (&acc)[2][2][4][2], const Unit& u, int wr, int wc, int fr, int fq) const {
;     ...
;             for (int m = 0; m < 4; ++m) { const int row = row0 + ai * HALF + m * 16;
;                 const float rs = __builtin_amdgcn_rsqf(ssq[row] * (1.0f / 1024.0f) + 1e-6f) * sc;
;                 const int b = row >> 12, tl = row & 4095, tile = tl >> 5, r = tl & 31;
; #pragma unroll
;                 for (int bj = 0; bj < 2; ++bj) { const int cc = (colt & 1023) + bj * HALF + wc * 32 + 8 * fq, h = cc >> 6, d8 = cc & 63, bh = b * 16 + h;
;                     const f32x4 v0 = acc[ai][bj][m][0] * rs, v1 = acc[ai][bj][m][1] * rs;
;                     u32x4 w; w.x = cvt_pk_bf16(v0[0], v0[1]); w.y = cvt_pk_bf16(v0[2], v0[3]); w.z = cvt_pk_bf16(v1[0], v1[1]); w.w = cvt_pk_bf16(v1[2], v1[3]);
;                     if (region < 2) { const int ks = d8 >> 4, hh = (d8 >> 3) & 1;
;                         *(u32x4*)(base + ((size_t)(((bh * 128 + tile) * 4 + ks) * 64 + hh * 32 + r) << 3)) = w;
;                     } else { const int dt = d8 >> 5, g = (d8 >> 3) & 3; bf16_t* p = base + ((size_t)((((bh * 128 + tile) * 2 + dt) * 4 + g) * 64 + r) << 2);
;                         *(unsigned long long*)p = (unsigned long long)w.x | ((unsigned long long)w.y << 32);
;                         *(unsigned long long*)(p + 128) = (unsigned long long)w.z | ((unsigned long long)w.w << 32); } }
.LBB0_509:
	s_nop 1
	v_or_b32_e32 v96, 32, v144
	v_ashrrev_i32_e32 v97, 31, v96
	v_lshl_add_u64 v[98:99], v[96:97], 2, s[8:9]
	global_load_dword v97, v[98:99], off
	s_and_b64 vcc, exec, s[4:5]
	s_mov_b64 s[26:27], -1
	s_waitcnt vmcnt(0)
	v_fmamk_f32 v97, v97, 0x3a800000, v165
	v_rsq_f32_e32 v99, v97
	v_bfe_u32 v97, v96, 5, 7
	v_lshl_or_b32 v98, v97, 3, s58
	v_mul_f32_e32 v96, v145, v99
	v_pk_mul_f32 v[100:101], v[90:91], v[96:97] op_sel_hi:[1,0]
	v_pk_mul_f32 v[90:91], v[88:89], v[96:97] op_sel_hi:[1,0]
	v_pk_mul_f32 v[94:95], v[94:95], v[96:97] op_sel_hi:[1,0]
	v_pk_mul_f32 v[92:93], v[92:93], v[96:97] op_sel_hi:[1,0]
	s_nop 0
	s_cmp_eq_u32 s95, 0
	s_cbranch_scc1 .Lsilu_skip_4
	v_mul_f32_e32 v200, 0xbfb8aa3b, v92
	v_mul_f32_e32 v201, 0xbfb8aa3b, v93
	v_mul_f32_e32 v202, 0xbfb8aa3b, v94
	v_mul_f32_e32 v203, 0xbfb8aa3b, v95
	v_mul_f32_e32 v204, 0xbfb8aa3b, v90
	v_mul_f32_e32 v205, 0xbfb8aa3b, v91
	v_mul_f32_e32 v206, 0xbfb8aa3b, v100
	v_mul_f32_e32 v207, 0xbfb8aa3b, v101
	v_exp_f32_e32 v200, v200
	v_exp_f32_e32 v201, v201
	v_exp_f32_e32 v202, v202
	v_exp_f32_e32 v203, v203
	v_exp_f32_e32 v204, v204
	v_exp_f32_e32 v205, v205
	v_exp_f32_e32 v206, v206
	v_exp_f32_e32 v207, v207
	v_add_f32_e32 v200, 1.0, v200
	v_add_f32_e32 v201, 1.0, v201
	v_add_f32_e32 v202, 1.0, v202
	v_add_f32_e32 v203, 1.0, v203
	v_add_f32_e32 v204, 1.0, v204
	v_add_f32_e32 v205, 1.0, v205
	v_add_f32_e32 v206, 1.0, v206
	v_add_f32_e32 v207, 1.0, v207
	v_rcp_f32_e32 v200, v200
	v_rcp_f32_e32 v201, v201
	v_rcp_f32_e32 v202, v202
	v_rcp_f32_e32 v203, v203
	v_rcp_f32_e32 v204, v204
	v_rcp_f32_e32 v205, v205
	v_rcp_f32_e32 v206, v206
	v_rcp_f32_e32 v207, v207
	v_mul_f32_e32 v92, v200, v92
	v_mul_f32_e32 v93, v201, v93
	v_mul_f32_e32 v94, v202, v94
	v_mul_f32_e32 v95, v203, v95
	v_mul_f32_e32 v90, v204, v90
	v_mul_f32_e32 v91, v205, v91
	v_mul_f32_e32 v100, v206, v100
	v_mul_f32_e32 v101, v207, v101
.Lsilu_skip_4:
	v_cvt_pk_bf16_f32 v88, v92, v93
	v_cvt_pk_bf16_f32 v89, v94, v95
	v_cvt_pk_bf16_f32 v90, v90, v91
	v_cvt_pk_bf16_f32 v91, v100, v101
	s_cbranch_vccnz .LBB0_511
	s_lshl_b32 s26, s30, 10
	v_or3_b32 v92, v98, s26, v154
	v_lshl_or_b32 v92, v92, 6, v162
	v_ashrrev_i32_e32 v93, 31, v92
	v_lshl_add_u64 v[92:93], v[92:93], 3, s[24:25]
	s_mov_b64 s[26:27], 0
	global_store_dwordx2 v[92:93], v[88:89], off
	global_store_dwordx2 v[92:93], v[90:91], off offset:256

; __device__ __forceinline__ unsigned cvt_pk_bf16(float lo, float hi) { unsigned r; asm volatile("v_cvt_pk_bf16_f32 %0, %1, %2" : "=v"(r) : "v"(lo), "v"(hi)); return r; }
;     __device__ __forceinline__ void operator()(const f32x4 (&acc)[2][2][4][2], const Unit& u, int wr, int wc, int fr, int fq) const {
;     ...
;             for (int m = 0; m < 4; ++m) { const int row = row0 + ai * HALF + m * 16;
;                 const float rs = __builtin_amdgcn_rsqf(ssq[row] * (1.0f / 1024.0f) + 1e-6f) * sc;
;                 const int b = row >> 12, tl = row & 4095, tile = tl >> 5, r = tl & 31;
; #pragma unroll
;                 for (int bj = 0; bj < 2; ++bj) { const int cc = (colt & 1023) + bj * HALF + wc * 32 + 8 * fq, h = cc >> 6, d8 = cc & 63, bh = b * 16 + h;
;                     const f32x4 v0 = acc[ai][bj][m][0] * rs, v1 = acc[ai][bj][m][1] * rs;
;                     u32x4 w; w.x = cvt_pk_bf16(v0[0], v0[1]); w.y = cvt_pk_bf16(v0[2], v0[3]); w.z = cvt_pk_bf16(v1[0], v1[1]); w.w = cvt_pk_bf16(v1[2], v1[3]);
;                     if (region < 2) { const int ks = d8 >> 4, hh = (d8 >> 3) & 1;
;                         *(u32x4*)(base + ((size_t)(((bh * 128 + tile) * 4 + ks) * 64 + hh * 32 + r) << 3)) = w;
;                     } else { const int dt = d8 >> 5, g = (d8 >> 3) & 3; bf16_t* p = base + ((size_t)((((bh * 128 + tile) * 2 + dt) * 4 + g) * 64 + r) << 2);
;                         *(unsigned long long*)p = (unsigned long long)w.x | ((unsigned long long)w.y << 32);
;                         *(unsigned long long*)(p + 128) = (unsigned long long)w.z | ((unsigned long long)w.w << 32); } }
.LBB0_513:
	v_mov_b32_e32 v97, v96
	s_nop 0
	v_mov_b32_e32 v88, v96
	v_mov_b32_e32 v89, v96
	v_pk_mul_f32 v[86:87], v[86:87], v[88:89]
	v_pk_mul_f32 v[88:89], v[82:83], v[88:89]
	v_pk_mul_f32 v[82:83], v[80:81], v[96:97]
	s_and_b64 vcc, exec, s[4:5]
	s_mov_b64 s[26:27], -1
	v_pk_mul_f32 v[84:85], v[84:85], v[96:97]
	s_nop 0
	s_cmp_eq_u32 s95, 0
	s_cbranch_scc1 .Lsilu_skip_5
	v_mul_f32_e32 v200, 0xbfb8aa3b, v84
	v_mul_f32_e32 v201, 0xbfb8aa3b, v85
	v_mul_f32_e32 v202, 0xbfb8aa3b, v86
	v_mul_f32_e32 v203, 0xbfb8aa3b, v87
	v_mul_f32_e32 v204, 0xbfb8aa3b, v82
	v_mul_f32_e32 v205, 0xbfb8aa3b, v83
	v_mul_f32_e32 v206, 0xbfb8aa3b, v88
	v_mul_f32_e32 v207, 0xbfb8aa3b, v89
	v_exp_f32_e32 v200, v200
	v_exp_f32_e32 v201, v201
	v_exp_f32_e32 v202, v202
	v_exp_f32_e32 v203, v203
	v_exp_f32_e32 v204, v204
	v_exp_f32_e32 v205, v205
	v_exp_f32_e32 v206, v206
	v_exp_f32_e32 v207, v207
	v_add_f32_e32 v200, 1.0, v200
	v_add_f32_e32 v201, 1.0, v201
	v_add_f32_e32 v202, 1.0, v202
	v_add_f32_e32 v203, 1.0, v203
	v_add_f32_e32 v204, 1.0, v204
	v_add_f32_e32 v205, 1.0, v205
	v_add_f32_e32 v206, 1.0, v206
	v_add_f32_e32 v207, 1.0, v207
	v_rcp_f32_e32 v200, v200
	v_rcp_f32_e32 v201, v201
	v_rcp_f32_e32 v202, v202
	v_rcp_f32_e32 v203, v203
	v_rcp_f32_e32 v204, v204
	v_rcp_f32_e32 v205, v205
	v_rcp_f32_e32 v206, v206
	v_rcp_f32_e32 v207, v207
	v_mul_f32_e32 v84, v200, v84
	v_mul_f32_e32 v85, v201, v85
	v_mul_f32_e32 v86, v202, v86
	v_mul_f32_e32 v87, v203, v87
	v_mul_f32_e32 v82, v204, v82
	v_mul_f32_e32 v83, v205, v83
	v_mul_f32_e32 v88, v206, v88
	v_mul_f32_e32 v89, v207, v89
.Lsilu_skip_5:
	v_cvt_pk_bf16_f32 v80, v84, v85
	v_cvt_pk_bf16_f32 v81, v86, v87
	v_cvt_pk_bf16_f32 v82, v82, v83
	v_cvt_pk_bf16_f32 v83, v88, v89
	s_cbranch_vccnz .LBB0_515
	s_lshl_b32 s26, s28, 10
	v_or3_b32 v84, v98, s26, v154
	v_lshl_or_b32 v84, v84, 6, v162
	v_ashrrev_i32_e32 v85, 31, v84
	v_lshl_add_u64 v[84:85], v[84:85], 3, s[24:25]
	s_mov_b64 s[26:27], 0
	global_store_dwordx2 v[84:85], v[80:81], off
	global_store_dwordx2 v[84:85], v[82:83], off offset:256

; __device__ __forceinline__ unsigned cvt_pk_bf16(float lo, float hi) { unsigned r; asm volatile("v_cvt_pk_bf16_f32 %0, %1, %2" : "=v"(r) : "v"(lo), "v"(hi)); return r; }
;     __device__ __forceinline__ void operator()(const f32x4 (&acc)[2][2][4][2], const Unit& u, int wr, int wc, int fr, int fq) const {
;     ...
;             for (int m = 0; m < 4; ++m) { const int row = row0 + ai * HALF + m * 16;
;                 const float rs = __builtin_amdgcn_rsqf(ssq[row] * (1.0f / 1024.0f) + 1e-6f) * sc;
;                 const int b = row >> 12, tl = row & 4095, tile = tl >> 5, r = tl & 31;
; #pragma unroll
;                 for (int bj = 0; bj < 2; ++bj) { const int cc = (colt & 1023) + bj * HALF + wc * 32 + 8 * fq, h = cc >> 6, d8 = cc & 63, bh = b * 16 + h;
;                     const f32x4 v0 = acc[ai][bj][m][0] * rs, v1 = acc[ai][bj][m][1] * rs;
;                     u32x4 w; w.x = cvt_pk_bf16(v0[0], v0[1]); w.y = cvt_pk_bf16(v0[2], v0[3]); w.z = cvt_pk_bf16(v1[0], v1[1]); w.w = cvt_pk_bf16(v1[2], v1[3]);
;                     if (region < 2) { const int ks = d8 >> 4, hh = (d8 >> 3) & 1;
;                         *(u32x4*)(base + ((size_t)(((bh * 128 + tile) * 4 + ks) * 64 + hh * 32 + r) << 3)) = w;
;                     } else { const int dt = d8 >> 5, g = (d8 >> 3) & 3; bf16_t* p = base + ((size_t)((((bh * 128 + tile) * 2 + dt) * 4 + g) * 64 + r) << 2);
;                         *(unsigned long long*)p = (unsigned long long)w.x | ((unsigned long long)w.y << 32);
;                         *(unsigned long long*)(p + 128) = (unsigned long long)w.z | ((unsigned long long)w.w << 32); } }
.LBB0_517:
	s_nop 1
	v_or_b32_e32 v80, 48, v144
	v_ashrrev_i32_e32 v81, 31, v80
	v_lshl_add_u64 v[82:83], v[80:81], 2, s[8:9]
	global_load_dword v81, v[82:83], off
	s_and_b64 vcc, exec, s[4:5]
	s_mov_b64 s[26:27], -1
	s_waitcnt vmcnt(0)
	v_fmamk_f32 v81, v81, 0x3a800000, v165
	v_rsq_f32_e32 v83, v81
	v_bfe_u32 v81, v80, 5, 7
	v_lshl_or_b32 v82, v81, 3, s58
	v_mul_f32_e32 v80, v145, v83
	v_pk_mul_f32 v[84:85], v[74:75], v[80:81] op_sel_hi:[1,0]
	v_pk_mul_f32 v[74:75], v[72:73], v[80:81] op_sel_hi:[1,0]
	v_pk_mul_f32 v[78:79], v[78:79], v[80:81] op_sel_hi:[1,0]
	v_pk_mul_f32 v[76:77], v[76:77], v[80:81] op_sel_hi:[1,0]
	s_nop 0
	s_cmp_eq_u32 s95, 0
	s_cbranch_scc1 .Lsilu_skip_6
	v_mul_f32_e32 v200, 0xbfb8aa3b, v76
	v_mul_f32_e32 v201, 0xbfb8aa3b, v77
	v_mul_f32_e32 v202, 0xbfb8aa3b, v78
	v_mul_f32_e32 v203, 0xbfb8aa3b, v79
	v_mul_f32_e32 v204, 0xbfb8aa3b, v74
	v_mul_f32_e32 v205, 0xbfb8aa3b, v75
	v_mul_f32_e32 v206, 0xbfb8aa3b, v84
	v_mul_f32_e32 v207, 0xbfb8aa3b, v85
	v_exp_f32_e32 v200, v200
	v_exp_f32_e32 v201, v201
	v_exp_f32_e32 v202, v202
	v_exp_f32_e32 v203, v203
	v_exp_f32_e32 v204, v204
	v_exp_f32_e32 v205, v205
	v_exp_f32_e32 v206, v206
	v_exp_f32_e32 v207, v207
	v_add_f32_e32 v200, 1.0, v200
	v_add_f32_e32 v201, 1.0, v201
	v_add_f32_e32 v202, 1.0, v202
	v_add_f32_e32 v203, 1.0, v203
	v_add_f32_e32 v204, 1.0, v204
	v_add_f32_e32 v205, 1.0, v205
	v_add_f32_e32 v206, 1.0, v206
	v_add_f32_e32 v207, 1.0, v207
	v_rcp_f32_e32 v200, v200
	v_rcp_f32_e32 v201, v201
	v_rcp_f32_e32 v202, v202
	v_rcp_f32_e32 v203, v203
	v_rcp_f32_e32 v204, v204
	v_rcp_f32_e32 v205, v205
	v_rcp_f32_e32 v206, v206
	v_rcp_f32_e32 v207, v207
	v_mul_f32_e32 v76, v200, v76
	v_mul_f32_e32 v77, v201, v77
	v_mul_f32_e32 v78, v202, v78
	v_mul_f32_e32 v79, v203, v79
	v_mul_f32_e32 v74, v204, v74
	v_mul_f32_e32 v75, v205, v75
	v_mul_f32_e32 v84, v206, v84
	v_mul_f32_e32 v85, v207, v85
.Lsilu_skip_6:
	v_cvt_pk_bf16_f32 v72, v76, v77
	v_cvt_pk_bf16_f32 v73, v78, v79
	v_cvt_pk_bf16_f32 v74, v74, v75
	v_cvt_pk_bf16_f32 v75, v84, v85
	s_cbranch_vccnz .LBB0_519
	s_lshl_b32 s26, s30, 10
	v_or3_b32 v76, v82, s26, v154
	v_lshl_or_b32 v76, v76, 6, v158
	v_ashrrev_i32_e32 v77, 31, v76
	v_lshl_add_u64 v[76:77], v[76:77], 3, s[24:25]
	s_mov_b64 s[26:27], 0
	global_store_dwordx2 v[76:77], v[72:73], off
	global_store_dwordx2 v[76:77], v[74:75], off offset:256

; __device__ __forceinline__ unsigned cvt_pk_bf16(float lo, float hi) { unsigned r; asm volatile("v_cvt_pk_bf16_f32 %0, %1, %2" : "=v"(r) : "v"(lo), "v"(hi)); return r; }
;     __device__ __forceinline__ void operator()(const f32x4 (&acc)[2][2][4][2], const Unit& u, int wr, int wc, int fr, int fq) const {
;     ...
;             for (int m = 0; m < 4; ++m) { const int row = row0 + ai * HALF + m * 16;
;                 const float rs = __builtin_amdgcn_rsqf(ssq[row] * (1.0f / 1024.0f) + 1e-6f) * sc;
;                 const int b = row >> 12, tl = row & 4095, tile = tl >> 5, r = tl & 31;
; #pragma unroll
;                 for (int bj = 0; bj < 2; ++bj) { const int cc = (colt & 1023) + bj * HALF + wc * 32 + 8 * fq, h = cc >> 6, d8 = cc & 63, bh = b * 16 + h;
;                     const f32x4 v0 = acc[ai][bj][m][0] * rs, v1 = acc[ai][bj][m][1] * rs;
;                     u32x4 w; w.x = cvt_pk_bf16(v0[0], v0[1]); w.y = cvt_pk_bf16(v0[2], v0[3]); w.z = cvt_pk_bf16(v1[0], v1[1]); w.w = cvt_pk_bf16(v1[2], v1[3]);
;                     if (region < 2) { const int ks = d8 >> 4, hh = (d8 >> 3) & 1;
;                         *(u32x4*)(base + ((size_t)(((bh * 128 + tile) * 4 + ks) * 64 + hh * 32 + r) << 3)) = w;
;                     } else { const int dt = d8 >> 5, g = (d8 >> 3) & 3; bf16_t* p = base + ((size_t)((((bh * 128 + tile) * 2 + dt) * 4 + g) * 64 + r) << 2);
;                         *(unsigned long long*)p = (unsigned long long)w.x | ((unsigned long long)w.y << 32);
;                         *(unsigned long long*)(p + 128) = (unsigned long long)w.z | ((unsigned long long)w.w << 32); } }
.LBB0_521:
	v_mov_b32_e32 v81, v80
	s_nop 0
	v_mov_b32_e32 v72, v80
	v_mov_b32_e32 v73, v80
	v_pk_mul_f32 v[70:71], v[70:71], v[72:73]
	v_pk_mul_f32 v[72:73], v[66:67], v[72:73]
	v_pk_mul_f32 v[66:67], v[64:65], v[80:81]
	s_and_b64 vcc, exec, s[4:5]
	s_mov_b64 s[26:27], -1
	v_pk_mul_f32 v[68:69], v[68:69], v[80:81]
	s_nop 0
	s_cmp_eq_u32 s95, 0
	s_cbranch_scc1 .Lsilu_skip_7
	v_mul_f32_e32 v200, 0xbfb8aa3b, v68
	v_mul_f32_e32 v201, 0xbfb8aa3b, v69
	v_mul_f32_e32 v202, 0xbfb8aa3b, v70
	v_mul_f32_e32 v203, 0xbfb8aa3b, v71
	v_mul_f32_e32 v204, 0xbfb8aa3b, v66
	v_mul_f32_e32 v205, 0xbfb8aa3b, v67
	v_mul_f32_e32 v206, 0xbfb8aa3b, v72
	v_mul_f32_e32 v207, 0xbfb8aa3b, v73
	v_exp_f32_e32 v200, v200
	v_exp_f32_e32 v201, v201
	v_exp_f32_e32 v202, v202
	v_exp_f32_e32 v203, v203
	v_exp_f32_e32 v204, v204
	v_exp_f32_e32 v205, v205
	v_exp_f32_e32 v206, v206
	v_exp_f32_e32 v207, v207
	v_add_f32_e32 v200, 1.0, v200
	v_add_f32_e32 v201, 1.0, v201
	v_add_f32_e32 v202, 1.0, v202
	v_add_f32_e32 v203, 1.0, v203
	v_add_f32_e32 v204, 1.0, v204
	v_add_f32_e32 v205, 1.0, v205
	v_add_f32_e32 v206, 1.0, v206
	v_add_f32_e32 v207, 1.0, v207
	v_rcp_f32_e32 v200, v200
	v_rcp_f32_e32 v201, v201
	v_rcp_f32_e32 v202, v202
	v_rcp_f32_e32 v203, v203
	v_rcp_f32_e32 v204, v204
	v_rcp_f32_e32 v205, v205
	v_rcp_f32_e32 v206, v206
	v_rcp_f32_e32 v207, v207
	v_mul_f32_e32 v68, v200, v68
	v_mul_f32_e32 v69, v201, v69
	v_mul_f32_e32 v70, v202, v70
	v_mul_f32_e32 v71, v203, v71
	v_mul_f32_e32 v66, v204, v66
	v_mul_f32_e32 v67, v205, v67
	v_mul_f32_e32 v72, v206, v72
	v_mul_f32_e32 v73, v207, v73
.Lsilu_skip_7:
	v_cvt_pk_bf16_f32 v64, v68, v69
	v_cvt_pk_bf16_f32 v65, v70, v71
	v_cvt_pk_bf16_f32 v66, v66, v67
	v_cvt_pk_bf16_f32 v67, v72, v73
	s_cbranch_vccnz .LBB0_523
	s_lshl_b32 s26, s28, 10
	v_or3_b32 v68, v82, s26, v154
	v_lshl_or_b32 v68, v68, 6, v158
	v_ashrrev_i32_e32 v69, 31, v68
	v_lshl_add_u64 v[68:69], v[68:69], 3, s[24:25]
	s_mov_b64 s[26:27], 0
	global_store_dwordx2 v[68:69], v[64:65], off
	global_store_dwordx2 v[68:69], v[66:67], off offset:256

; __device__ __forceinline__ unsigned cvt_pk_bf16(float lo, float hi) { unsigned r; asm volatile("v_cvt_pk_bf16_f32 %0, %1, %2" : "=v"(r) : "v"(lo), "v"(hi)); return r; }
;     __device__ __forceinline__ void operator()(const f32x4 (&acc)[2][2][4][2], const Unit& u, int wr, int wc, int fr, int fq) const {
;     ...
;             for (int m = 0; m < 4; ++m) { const int row = row0 + ai * HALF + m * 16;
;                 const float rs = __builtin_amdgcn_rsqf(ssq[row] * (1.0f / 1024.0f) + 1e-6f) * sc;
;                 const int b = row >> 12, tl = row & 4095, tile = tl >> 5, r = tl & 31;
; #pragma unroll
;                 for (int bj = 0; bj < 2; ++bj) { const int cc = (colt & 1023) + bj * HALF + wc * 32 + 8 * fq, h = cc >> 6, d8 = cc & 63, bh = b * 16 + h;
;                     const f32x4 v0 = acc[ai][bj][m][0] * rs, v1 = acc[ai][bj][m][1] * rs;
;                     u32x4 w; w.x = cvt_pk_bf16(v0[0], v0[1]); w.y = cvt_pk_bf16(v0[2], v0[3]); w.z = cvt_pk_bf16(v1[0], v1[1]); w.w = cvt_pk_bf16(v1[2], v1[3]);
;                     if (region < 2) { const int ks = d8 >> 4, hh = (d8 >> 3) & 1;
;                         *(u32x4*)(base + ((size_t)(((bh * 128 + tile) * 4 + ks) * 64 + hh * 32 + r) << 3)) = w;
;                     } else { const int dt = d8 >> 5, g = (d8 >> 3) & 3; bf16_t* p = base + ((size_t)((((bh * 128 + tile) * 2 + dt) * 4 + g) * 64 + r) << 2);
;                         *(unsigned long long*)p = (unsigned long long)w.x | ((unsigned long long)w.y << 32);
;                         *(unsigned long long*)(p + 128) = (unsigned long long)w.z | ((unsigned long long)w.w << 32); } }
.LBB0_525:
	global_load_dword v64, v[146:147], off offset:512
	s_nop 0
	v_add_u32_e32 v65, 0x80, v144
	v_ashrrev_i32_e32 v66, 8, v65
	v_lshrrev_b32_e32 v65, 5, v65
	v_and_b32_e32 v67, -16, v66
	v_and_b32_e32 v65, 0x7e, v65
	v_or_b32_e32 v68, s17, v67
	s_mov_b64 s[26:27], -1
	s_and_b64 vcc, exec, s[4:5]
	v_lshl_or_b32 v66, v65, 3, s69
	s_waitcnt vmcnt(0)
	v_fmamk_f32 v64, v64, 0x3a800000, v165
	v_rsq_f32_e32 v64, v64
	s_nop 0
	v_mul_f32_e32 v64, v145, v64
	v_pk_mul_f32 v[60:61], v[60:61], v[64:65] op_sel_hi:[1,0]
	v_pk_mul_f32 v[70:71], v[58:59], v[64:65] op_sel_hi:[1,0]
	v_pk_mul_f32 v[58:59], v[56:57], v[64:65] op_sel_hi:[1,0]
	v_pk_mul_f32 v[62:63], v[62:63], v[64:65] op_sel_hi:[1,0]
	s_cmp_eq_u32 s95, 0
	s_cbranch_scc1 .Lsilu_skip_8
	v_mul_f32_e32 v200, 0xbfb8aa3b, v60
	v_mul_f32_e32 v201, 0xbfb8aa3b, v61
	v_mul_f32_e32 v202, 0xbfb8aa3b, v62
	v_mul_f32_e32 v203, 0xbfb8aa3b, v63
	v_mul_f32_e32 v204, 0xbfb8aa3b, v58
	v_mul_f32_e32 v205, 0xbfb8aa3b, v59
	v_mul_f32_e32 v206, 0xbfb8aa3b, v70
	v_mul_f32_e32 v207, 0xbfb8aa3b, v71
	v_exp_f32_e32 v200, v200
	v_exp_f32_e32 v201, v201
	v_exp_f32_e32 v202, v202
	v_exp_f32_e32 v203, v203
	v_exp_f32_e32 v204, v204
	v_exp_f32_e32 v205, v205
	v_exp_f32_e32 v206, v206
	v_exp_f32_e32 v207, v207
	v_add_f32_e32 v200, 1.0, v200
	v_add_f32_e32 v201, 1.0, v201
	v_add_f32_e32 v202, 1.0, v202
	v_add_f32_e32 v203, 1.0, v203
	v_add_f32_e32 v204, 1.0, v204
	v_add_f32_e32 v205, 1.0, v205
	v_add_f32_e32 v206, 1.0, v206
	v_add_f32_e32 v207, 1.0, v207
	v_rcp_f32_e32 v200, v200
	v_rcp_f32_e32 v201, v201
	v_rcp_f32_e32 v202, v202
	v_rcp_f32_e32 v203, v203
	v_rcp_f32_e32 v204, v204
	v_rcp_f32_e32 v205, v205
	v_rcp_f32_e32 v206, v206
	v_rcp_f32_e32 v207, v207
	v_mul_f32_e32 v60, v200, v60
	v_mul_f32_e32 v61, v201, v61
	v_mul_f32_e32 v62, v202, v62
	v_mul_f32_e32 v63, v203, v63
	v_mul_f32_e32 v58, v204, v58
	v_mul_f32_e32 v59, v205, v59
	v_mul_f32_e32 v70, v206, v70
	v_mul_f32_e32 v71, v207, v71
.Lsilu_skip_8:
	v_cvt_pk_bf16_f32 v56, v60, v61
	v_lshlrev_b32_e32 v61, 10, v68
	s_nop 0
	v_cvt_pk_bf16_f32 v57, v62, v63
	v_cvt_pk_bf16_f32 v58, v58, v59
	v_cvt_pk_bf16_f32 v59, v70, v71
	s_cbranch_vccnz .LBB0_527
	v_or3_b32 v60, v66, v61, v154
	v_lshl_or_b32 v62, v60, 6, v162
	v_ashrrev_i32_e32 v63, 31, v62
	v_lshl_add_u64 v[62:63], v[62:63], 3, s[24:25]
	s_mov_b64 s[26:27], 0
	global_store_dwordx2 v[62:63], v[56:57], off
	global_store_dwordx2 v[62:63], v[58:59], off offset:256

; __device__ __forceinline__ unsigned cvt_pk_bf16(float lo, float hi) { unsigned r; asm volatile("v_cvt_pk_bf16_f32 %0, %1, %2" : "=v"(r) : "v"(lo), "v"(hi)); return r; }
;     __device__ __forceinline__ void operator()(const f32x4 (&acc)[2][2][4][2], const Unit& u, int wr, int wc, int fr, int fq) const {
;     ...
;             for (int m = 0; m < 4; ++m) { const int row = row0 + ai * HALF + m * 16;
;                 const float rs = __builtin_amdgcn_rsqf(ssq[row] * (1.0f / 1024.0f) + 1e-6f) * sc;
;                 const int b = row >> 12, tl = row & 4095, tile = tl >> 5, r = tl & 31;
; #pragma unroll
;                 for (int bj = 0; bj < 2; ++bj) { const int cc = (colt & 1023) + bj * HALF + wc * 32 + 8 * fq, h = cc >> 6, d8 = cc & 63, bh = b * 16 + h;
;                     const f32x4 v0 = acc[ai][bj][m][0] * rs, v1 = acc[ai][bj][m][1] * rs;
;                     u32x4 w; w.x = cvt_pk_bf16(v0[0], v0[1]); w.y = cvt_pk_bf16(v0[2], v0[3]); w.z = cvt_pk_bf16(v1[0], v1[1]); w.w = cvt_pk_bf16(v1[2], v1[3]);
;                     if (region < 2) { const int ks = d8 >> 4, hh = (d8 >> 3) & 1;
;                         *(u32x4*)(base + ((size_t)(((bh * 128 + tile) * 4 + ks) * 64 + hh * 32 + r) << 3)) = w;
;                     } else { const int dt = d8 >> 5, g = (d8 >> 3) & 3; bf16_t* p = base + ((size_t)((((bh * 128 + tile) * 2 + dt) * 4 + g) * 64 + r) << 2);
;                         *(unsigned long long*)p = (unsigned long long)w.x | ((unsigned long long)w.y << 32);
;                         *(unsigned long long*)(p + 128) = (unsigned long long)w.z | ((unsigned long long)w.w << 32); } }
.LBB0_529:
	v_mov_b32_e32 v65, v64
	s_nop 0
	v_or_b32_e32 v56, s19, v67
	v_mov_b32_e32 v58, v64
	v_mov_b32_e32 v59, v64
	v_pk_mul_f32 v[52:53], v[52:53], v[64:65]
	v_pk_mul_f32 v[54:55], v[54:55], v[58:59]
	v_pk_mul_f32 v[58:59], v[50:51], v[58:59]
	v_pk_mul_f32 v[50:51], v[48:49], v[64:65]
	s_cmp_eq_u32 s95, 0
	s_cbranch_scc1 .Lsilu_skip_9
	v_mul_f32_e32 v200, 0xbfb8aa3b, v52
	v_mul_f32_e32 v201, 0xbfb8aa3b, v53
	v_mul_f32_e32 v202, 0xbfb8aa3b, v54
	v_mul_f32_e32 v203, 0xbfb8aa3b, v55
	v_mul_f32_e32 v204, 0xbfb8aa3b, v50
	v_mul_f32_e32 v205, 0xbfb8aa3b, v51
	v_mul_f32_e32 v206, 0xbfb8aa3b, v58
	v_mul_f32_e32 v207, 0xbfb8aa3b, v59
	v_exp_f32_e32 v200, v200
	v_exp_f32_e32 v201, v201
	v_exp_f32_e32 v202, v202
	v_exp_f32_e32 v203, v203
	v_exp_f32_e32 v204, v204
	v_exp_f32_e32 v205, v205
	v_exp_f32_e32 v206, v206
	v_exp_f32_e32 v207, v207
	v_add_f32_e32 v200, 1.0, v200
	v_add_f32_e32 v201, 1.0, v201
	v_add_f32_e32 v202, 1.0, v202
	v_add_f32_e32 v203, 1.0, v203
	v_add_f32_e32 v204, 1.0, v204
	v_add_f32_e32 v205, 1.0, v205
	v_add_f32_e32 v206, 1.0, v206
	v_add_f32_e32 v207, 1.0, v207
	v_rcp_f32_e32 v200, v200
	v_rcp_f32_e32 v201, v201
	v_rcp_f32_e32 v202, v202
	v_rcp_f32_e32 v203, v203
	v_rcp_f32_e32 v204, v204
	v_rcp_f32_e32 v205, v205
	v_rcp_f32_e32 v206, v206
	v_rcp_f32_e32 v207, v207
	v_mul_f32_e32 v52, v200, v52
	v_mul_f32_e32 v53, v201, v53
	v_mul_f32_e32 v54, v202, v54
	v_mul_f32_e32 v55, v203, v55
	v_mul_f32_e32 v50, v204, v50
	v_mul_f32_e32 v51, v205, v51
	v_mul_f32_e32 v58, v206, v58
	v_mul_f32_e32 v59, v207, v59
.Lsilu_skip_9:
	v_cvt_pk_bf16_f32 v48, v52, v53
	s_mov_b64 s[26:27], -1
	s_and_b64 vcc, exec, s[4:5]
	v_lshlrev_b32_e32 v53, 10, v56
	v_cvt_pk_bf16_f32 v49, v54, v55
	v_cvt_pk_bf16_f32 v50, v50, v51
	v_cvt_pk_bf16_f32 v51, v58, v59
	s_cbranch_vccnz .LBB0_531
	v_or3_b32 v52, v66, v53, v154
	v_lshl_or_b32 v54, v52, 6, v162
	v_ashrrev_i32_e32 v55, 31, v54
	v_lshl_add_u64 v[54:55], v[54:55], 3, s[24:25]
	s_mov_b64 s[26:27], 0
	global_store_dwordx2 v[54:55], v[48:49], off
	global_store_dwordx2 v[54:55], v[50:51], off offset:256

; __device__ __forceinline__ unsigned cvt_pk_bf16(float lo, float hi) { unsigned r; asm volatile("v_cvt_pk_bf16_f32 %0, %1, %2" : "=v"(r) : "v"(lo), "v"(hi)); return r; }
;     __device__ __forceinline__ void operator()(const f32x4 (&acc)[2][2][4][2], const Unit& u, int wr, int wc, int fr, int fq) const {
;     ...
;             for (int m = 0; m < 4; ++m) { const int row = row0 + ai * HALF + m * 16;
;                 const float rs = __builtin_amdgcn_rsqf(ssq[row] * (1.0f / 1024.0f) + 1e-6f) * sc;
;                 const int b = row >> 12, tl = row & 4095, tile = tl >> 5, r = tl & 31;
; #pragma unroll
;                 for (int bj = 0; bj < 2; ++bj) { const int cc = (colt & 1023) + bj * HALF + wc * 32 + 8 * fq, h = cc >> 6, d8 = cc & 63, bh = b * 16 + h;
;                     const f32x4 v0 = acc[ai][bj][m][0] * rs, v1 = acc[ai][bj][m][1] * rs;
;                     u32x4 w; w.x = cvt_pk_bf16(v0[0], v0[1]); w.y = cvt_pk_bf16(v0[2], v0[3]); w.z = cvt_pk_bf16(v1[0], v1[1]); w.w = cvt_pk_bf16(v1[2], v1[3]);
;                     if (region < 2) { const int ks = d8 >> 4, hh = (d8 >> 3) & 1;
;                         *(u32x4*)(base + ((size_t)(((bh * 128 + tile) * 4 + ks) * 64 + hh * 32 + r) << 3)) = w;
;                     } else { const int dt = d8 >> 5, g = (d8 >> 3) & 3; bf16_t* p = base + ((size_t)((((bh * 128 + tile) * 2 + dt) * 4 + g) * 64 + r) << 2);
;                         *(unsigned long long*)p = (unsigned long long)w.x | ((unsigned long long)w.y << 32);
;                         *(unsigned long long*)(p + 128) = (unsigned long long)w.z | ((unsigned long long)w.w << 32); } }
.LBB0_533:
	global_load_dword v48, v[146:147], off offset:576
	s_nop 0
	v_add_u32_e32 v49, 0x90, v144
	v_lshrrev_b32_e32 v49, 5, v49
	v_and_b32_e32 v49, 0x7e, v49
	s_and_b64 vcc, exec, s[4:5]
	v_lshl_or_b32 v50, v49, 3, s69
	s_mov_b64 s[26:27], -1
	s_waitcnt vmcnt(0)
	v_fmamk_f32 v48, v48, 0x3a800000, v165
	v_rsq_f32_e32 v48, v48
	s_nop 0
	v_mul_f32_e32 v48, v145, v48
	v_pk_mul_f32 v[54:55], v[42:43], v[48:49] op_sel_hi:[1,0]
	v_pk_mul_f32 v[42:43], v[40:41], v[48:49] op_sel_hi:[1,0]
	v_pk_mul_f32 v[46:47], v[46:47], v[48:49] op_sel_hi:[1,0]
	v_pk_mul_f32 v[44:45], v[44:45], v[48:49] op_sel_hi:[1,0]
	s_nop 0
	s_cmp_eq_u32 s95, 0
	s_cbranch_scc1 .Lsilu_skip_10
	v_mul_f32_e32 v200, 0xbfb8aa3b, v44
	v_mul_f32_e32 v201, 0xbfb8aa3b, v45
	v_mul_f32_e32 v202, 0xbfb8aa3b, v46
	v_mul_f32_e32 v203, 0xbfb8aa3b, v47
	v_mul_f32_e32 v204, 0xbfb8aa3b, v42
	v_mul_f32_e32 v205, 0xbfb8aa3b, v43
	v_mul_f32_e32 v206, 0xbfb8aa3b, v54
	v_mul_f32_e32 v207, 0xbfb8aa3b, v55
	v_exp_f32_e32 v200, v200
	v_exp_f32_e32 v201, v201
	v_exp_f32_e32 v202, v202
	v_exp_f32_e32 v203, v203
	v_exp_f32_e32 v204, v204
	v_exp_f32_e32 v205, v205
	v_exp_f32_e32 v206, v206
	v_exp_f32_e32 v207, v207
	v_add_f32_e32 v200, 1.0, v200
	v_add_f32_e32 v201, 1.0, v201
	v_add_f32_e32 v202, 1.0, v202
	v_add_f32_e32 v203, 1.0, v203
	v_add_f32_e32 v204, 1.0, v204
	v_add_f32_e32 v205, 1.0, v205
	v_add_f32_e32 v206, 1.0, v206
	v_add_f32_e32 v207, 1.0, v207
	v_rcp_f32_e32 v200, v200
	v_rcp_f32_e32 v201, v201
	v_rcp_f32_e32 v202, v202
	v_rcp_f32_e32 v203, v203
	v_rcp_f32_e32 v204, v204
	v_rcp_f32_e32 v205, v205
	v_rcp_f32_e32 v206, v206
	v_rcp_f32_e32 v207, v207
	v_mul_f32_e32 v44, v200, v44
	v_mul_f32_e32 v45, v201, v45
	v_mul_f32_e32 v46, v202, v46
	v_mul_f32_e32 v47, v203, v47
	v_mul_f32_e32 v42, v204, v42
	v_mul_f32_e32 v43, v205, v43
	v_mul_f32_e32 v54, v206, v54
	v_mul_f32_e32 v55, v207, v55
.Lsilu_skip_10:
	v_cvt_pk_bf16_f32 v40, v44, v45
	v_cvt_pk_bf16_f32 v41, v46, v47
	v_cvt_pk_bf16_f32 v42, v42, v43
	v_cvt_pk_bf16_f32 v43, v54, v55
	s_cbranch_vccnz .LBB0_535
	v_or3_b32 v44, v50, v61, v154
	v_lshl_or_b32 v44, v44, 6, v158
	v_ashrrev_i32_e32 v45, 31, v44
	v_lshl_add_u64 v[44:45], v[44:45], 3, s[24:25]
	s_mov_b64 s[26:27], 0
	global_store_dwordx2 v[44:45], v[40:41], off
	global_store_dwordx2 v[44:45], v[42:43], off offset:256

; __device__ __forceinline__ unsigned cvt_pk_bf16(float lo, float hi) { unsigned r; asm volatile("v_cvt_pk_bf16_f32 %0, %1, %2" : "=v"(r) : "v"(lo), "v"(hi)); return r; }
;     __device__ __forceinline__ void operator()(const f32x4 (&acc)[2][2][4][2], const Unit& u, int wr, int wc, int fr, int fq) const {
;     ...
;             for (int m = 0; m < 4; ++m) { const int row = row0 + ai * HALF + m * 16;
;                 const float rs = __builtin_amdgcn_rsqf(ssq[row] * (1.0f / 1024.0f) + 1e-6f) * sc;
;                 const int b = row >> 12, tl = row & 4095, tile = tl >> 5, r = tl & 31;
; #pragma unroll
;                 for (int bj = 0; bj < 2; ++bj) { const int cc = (colt & 1023) + bj * HALF + wc * 32 + 8 * fq, h = cc >> 6, d8 = cc & 63, bh = b * 16 + h;
;                     const f32x4 v0 = acc[ai][bj][m][0] * rs, v1 = acc[ai][bj][m][1] * rs;
;                     u32x4 w; w.x = cvt_pk_bf16(v0[0], v0[1]); w.y = cvt_pk_bf16(v0[2], v0[3]); w.z = cvt_pk_bf16(v1[0], v1[1]); w.w = cvt_pk_bf16(v1[2], v1[3]);
;                     if (region < 2) { const int ks = d8 >> 4, hh = (d8 >> 3) & 1;
;                         *(u32x4*)(base + ((size_t)(((bh * 128 + tile) * 4 + ks) * 64 + hh * 32 + r) << 3)) = w;
;                     } else { const int dt = d8 >> 5, g = (d8 >> 3) & 3; bf16_t* p = base + ((size_t)((((bh * 128 + tile) * 2 + dt) * 4 + g) * 64 + r) << 2);
;                         *(unsigned long long*)p = (unsigned long long)w.x | ((unsigned long long)w.y << 32);
;                         *(unsigned long long*)(p + 128) = (unsigned long long)w.z | ((unsigned long long)w.w << 32); } }
.LBB0_537:
	v_mov_b32_e32 v49, v48
	s_nop 0
	v_mov_b32_e32 v40, v48
	v_mov_b32_e32 v41, v48
	v_pk_mul_f32 v[38:39], v[38:39], v[40:41]
	v_pk_mul_f32 v[40:41], v[34:35], v[40:41]
	v_pk_mul_f32 v[34:35], v[32:33], v[48:49]
	s_and_b64 vcc, exec, s[4:5]
	s_mov_b64 s[26:27], -1
	v_pk_mul_f32 v[36:37], v[36:37], v[48:49]
	s_nop 0
	s_cmp_eq_u32 s95, 0
	s_cbranch_scc1 .Lsilu_skip_11
	v_mul_f32_e32 v200, 0xbfb8aa3b, v36
	v_mul_f32_e32 v201, 0xbfb8aa3b, v37
	v_mul_f32_e32 v202, 0xbfb8aa3b, v38
	v_mul_f32_e32 v203, 0xbfb8aa3b, v39
	v_mul_f32_e32 v204, 0xbfb8aa3b, v34
	v_mul_f32_e32 v205, 0xbfb8aa3b, v35
	v_mul_f32_e32 v206, 0xbfb8aa3b, v40
	v_mul_f32_e32 v207, 0xbfb8aa3b, v41
	v_exp_f32_e32 v200, v200
	v_exp_f32_e32 v201, v201
	v_exp_f32_e32 v202, v202
	v_exp_f32_e32 v203, v203
	v_exp_f32_e32 v204, v204
	v_exp_f32_e32 v205, v205
	v_exp_f32_e32 v206, v206
	v_exp_f32_e32 v207, v207
	v_add_f32_e32 v200, 1.0, v200
	v_add_f32_e32 v201, 1.0, v201
	v_add_f32_e32 v202, 1.0, v202
	v_add_f32_e32 v203, 1.0, v203
	v_add_f32_e32 v204, 1.0, v204
	v_add_f32_e32 v205, 1.0, v205
	v_add_f32_e32 v206, 1.0, v206
	v_add_f32_e32 v207, 1.0, v207
	v_rcp_f32_e32 v200, v200
	v_rcp_f32_e32 v201, v201
	v_rcp_f32_e32 v202, v202
	v_rcp_f32_e32 v203, v203
	v_rcp_f32_e32 v204, v204
	v_rcp_f32_e32 v205, v205
	v_rcp_f32_e32 v206, v206
	v_rcp_f32_e32 v207, v207
	v_mul_f32_e32 v36, v200, v36
	v_mul_f32_e32 v37, v201, v37
	v_mul_f32_e32 v38, v202, v38
	v_mul_f32_e32 v39, v203, v39
	v_mul_f32_e32 v34, v204, v34
	v_mul_f32_e32 v35, v205, v35
	v_mul_f32_e32 v40, v206, v40
	v_mul_f32_e32 v41, v207, v41
.Lsilu_skip_11:
	v_cvt_pk_bf16_f32 v32, v36, v37
	v_cvt_pk_bf16_f32 v33, v38, v39
	v_cvt_pk_bf16_f32 v34, v34, v35
	v_cvt_pk_bf16_f32 v35, v40, v41
	s_cbranch_vccnz .LBB0_539
	v_or3_b32 v36, v50, v53, v154
	v_lshl_or_b32 v36, v36, 6, v158
	v_ashrrev_i32_e32 v37, 31, v36
	v_lshl_add_u64 v[36:37], v[36:37], 3, s[24:25]
	s_mov_b64 s[26:27], 0
	global_store_dwordx2 v[36:37], v[32:33], off
	global_store_dwordx2 v[36:37], v[34:35], off offset:256

; __device__ __forceinline__ unsigned cvt_pk_bf16(float lo, float hi) { unsigned r; asm volatile("v_cvt_pk_bf16_f32 %0, %1, %2" : "=v"(r) : "v"(lo), "v"(hi)); return r; }
;     __device__ __forceinline__ void operator()(const f32x4 (&acc)[2][2][4][2], const Unit& u, int wr, int wc, int fr, int fq) const {
;     ...
;             for (int m = 0; m < 4; ++m) { const int row = row0 + ai * HALF + m * 16;
;                 const float rs = __builtin_amdgcn_rsqf(ssq[row] * (1.0f / 1024.0f) + 1e-6f) * sc;
;                 const int b = row >> 12, tl = row & 4095, tile = tl >> 5, r = tl & 31;
; #pragma unroll
;                 for (int bj = 0; bj < 2; ++bj) { const int cc = (colt & 1023) + bj * HALF + wc * 32 + 8 * fq, h = cc >> 6, d8 = cc & 63, bh = b * 16 + h;
;                     const f32x4 v0 = acc[ai][bj][m][0] * rs, v1 = acc[ai][bj][m][1] * rs;
;                     u32x4 w; w.x = cvt_pk_bf16(v0[0], v0[1]); w.y = cvt_pk_bf16(v0[2], v0[3]); w.z = cvt_pk_bf16(v1[0], v1[1]); w.w = cvt_pk_bf16(v1[2], v1[3]);
;                     if (region < 2) { const int ks = d8 >> 4, hh = (d8 >> 3) & 1;
;                         *(u32x4*)(base + ((size_t)(((bh * 128 + tile) * 4 + ks) * 64 + hh * 32 + r) << 3)) = w;
;                     } else { const int dt = d8 >> 5, g = (d8 >> 3) & 3; bf16_t* p = base + ((size_t)((((bh * 128 + tile) * 2 + dt) * 4 + g) * 64 + r) << 2);
;                         *(unsigned long long*)p = (unsigned long long)w.x | ((unsigned long long)w.y << 32);
;                         *(unsigned long long*)(p + 128) = (unsigned long long)w.z | ((unsigned long long)w.w << 32); } }
.LBB0_541:
	global_load_dword v32, v[146:147], off offset:640
	s_nop 0
	v_add_u32_e32 v33, 0xa0, v144
	v_bfe_u32 v33, v33, 5, 7
	s_and_b64 vcc, exec, s[4:5]
	v_lshl_or_b32 v34, v33, 3, s69
	s_mov_b64 s[26:27], -1
	s_waitcnt vmcnt(0)
	v_fmamk_f32 v32, v32, 0x3a800000, v165
	v_rsq_f32_e32 v32, v32
	s_nop 0
	v_mul_f32_e32 v32, v145, v32
	v_pk_mul_f32 v[36:37], v[26:27], v[32:33] op_sel_hi:[1,0]
	v_pk_mul_f32 v[26:27], v[24:25], v[32:33] op_sel_hi:[1,0]
	v_pk_mul_f32 v[30:31], v[30:31], v[32:33] op_sel_hi:[1,0]
	v_pk_mul_f32 v[28:29], v[28:29], v[32:33] op_sel_hi:[1,0]
	s_nop 0
	s_cmp_eq_u32 s95, 0
	s_cbranch_scc1 .Lsilu_skip_12
	v_mul_f32_e32 v200, 0xbfb8aa3b, v28
	v_mul_f32_e32 v201, 0xbfb8aa3b, v29
	v_mul_f32_e32 v202, 0xbfb8aa3b, v30
	v_mul_f32_e32 v203, 0xbfb8aa3b, v31
	v_mul_f32_e32 v204, 0xbfb8aa3b, v26
	v_mul_f32_e32 v205, 0xbfb8aa3b, v27
	v_mul_f32_e32 v206, 0xbfb8aa3b, v36
	v_mul_f32_e32 v207, 0xbfb8aa3b, v37
	v_exp_f32_e32 v200, v200
	v_exp_f32_e32 v201, v201
	v_exp_f32_e32 v202, v202
	v_exp_f32_e32 v203, v203
	v_exp_f32_e32 v204, v204
	v_exp_f32_e32 v205, v205
	v_exp_f32_e32 v206, v206
	v_exp_f32_e32 v207, v207
	v_add_f32_e32 v200, 1.0, v200
	v_add_f32_e32 v201, 1.0, v201
	v_add_f32_e32 v202, 1.0, v202
	v_add_f32_e32 v203, 1.0, v203
	v_add_f32_e32 v204, 1.0, v204
	v_add_f32_e32 v205, 1.0, v205
	v_add_f32_e32 v206, 1.0, v206
	v_add_f32_e32 v207, 1.0, v207
	v_rcp_f32_e32 v200, v200
	v_rcp_f32_e32 v201, v201
	v_rcp_f32_e32 v202, v202
	v_rcp_f32_e32 v203, v203
	v_rcp_f32_e32 v204, v204
	v_rcp_f32_e32 v205, v205
	v_rcp_f32_e32 v206, v206
	v_rcp_f32_e32 v207, v207
	v_mul_f32_e32 v28, v200, v28
	v_mul_f32_e32 v29, v201, v29
	v_mul_f32_e32 v30, v202, v30
	v_mul_f32_e32 v31, v203, v31
	v_mul_f32_e32 v26, v204, v26
	v_mul_f32_e32 v27, v205, v27
	v_mul_f32_e32 v36, v206, v36
	v_mul_f32_e32 v37, v207, v37
.Lsilu_skip_12:
	v_cvt_pk_bf16_f32 v24, v28, v29
	v_cvt_pk_bf16_f32 v25, v30, v31
	v_cvt_pk_bf16_f32 v26, v26, v27
	v_cvt_pk_bf16_f32 v27, v36, v37
	s_cbranch_vccnz .LBB0_543
	v_or3_b32 v28, v34, v61, v154
	v_lshl_or_b32 v28, v28, 6, v162
	v_ashrrev_i32_e32 v29, 31, v28
	v_lshl_add_u64 v[28:29], v[28:29], 3, s[24:25]
	s_mov_b64 s[26:27], 0
	global_store_dwordx2 v[28:29], v[24:25], off
	global_store_dwordx2 v[28:29], v[26:27], off offset:256

; __device__ __forceinline__ unsigned cvt_pk_bf16(float lo, float hi) { unsigned r; asm volatile("v_cvt_pk_bf16_f32 %0, %1, %2" : "=v"(r) : "v"(lo), "v"(hi)); return r; }
;     __device__ __forceinline__ void operator()(const f32x4 (&acc)[2][2][4][2], const Unit& u, int wr, int wc, int fr, int fq) const {
;     ...
;             for (int m = 0; m < 4; ++m) { const int row = row0 + ai * HALF + m * 16;
;                 const float rs = __builtin_amdgcn_rsqf(ssq[row] * (1.0f / 1024.0f) + 1e-6f) * sc;
;                 const int b = row >> 12, tl = row & 4095, tile = tl >> 5, r = tl & 31;
; #pragma unroll
;                 for (int bj = 0; bj < 2; ++bj) { const int cc = (colt & 1023) + bj * HALF + wc * 32 + 8 * fq, h = cc >> 6, d8 = cc & 63, bh = b * 16 + h;
;                     const f32x4 v0 = acc[ai][bj][m][0] * rs, v1 = acc[ai][bj][m][1] * rs;
;                     u32x4 w; w.x = cvt_pk_bf16(v0[0], v0[1]); w.y = cvt_pk_bf16(v0[2], v0[3]); w.z = cvt_pk_bf16(v1[0], v1[1]); w.w = cvt_pk_bf16(v1[2], v1[3]);
;                     if (region < 2) { const int ks = d8 >> 4, hh = (d8 >> 3) & 1;
;                         *(u32x4*)(base + ((size_t)(((bh * 128 + tile) * 4 + ks) * 64 + hh * 32 + r) << 3)) = w;
;                     } else { const int dt = d8 >> 5, g = (d8 >> 3) & 3; bf16_t* p = base + ((size_t)((((bh * 128 + tile) * 2 + dt) * 4 + g) * 64 + r) << 2);
;                         *(unsigned long long*)p = (unsigned long long)w.x | ((unsigned long long)w.y << 32);
;                         *(unsigned long long*)(p + 128) = (unsigned long long)w.z | ((unsigned long long)w.w << 32); } }
.LBB0_545:
	v_mov_b32_e32 v33, v32
	s_nop 0
	v_mov_b32_e32 v24, v32
	v_mov_b32_e32 v25, v32
	v_pk_mul_f32 v[22:23], v[22:23], v[24:25]
	v_pk_mul_f32 v[24:25], v[18:19], v[24:25]
	v_pk_mul_f32 v[18:19], v[16:17], v[32:33]
	s_and_b64 vcc, exec, s[4:5]
	s_mov_b64 s[26:27], -1
	v_pk_mul_f32 v[20:21], v[20:21], v[32:33]
	s_nop 0
	s_cmp_eq_u32 s95, 0
	s_cbranch_scc1 .Lsilu_skip_13
	v_mul_f32_e32 v200, 0xbfb8aa3b, v20
	v_mul_f32_e32 v201, 0xbfb8aa3b, v21
	v_mul_f32_e32 v202, 0xbfb8aa3b, v22
	v_mul_f32_e32 v203, 0xbfb8aa3b, v23
	v_mul_f32_e32 v204, 0xbfb8aa3b, v18
	v_mul_f32_e32 v205, 0xbfb8aa3b, v19
	v_mul_f32_e32 v206, 0xbfb8aa3b, v24
	v_mul_f32_e32 v207, 0xbfb8aa3b, v25
	v_exp_f32_e32 v200, v200
	v_exp_f32_e32 v201, v201
	v_exp_f32_e32 v202, v202
	v_exp_f32_e32 v203, v203
	v_exp_f32_e32 v204, v204
	v_exp_f32_e32 v205, v205
	v_exp_f32_e32 v206, v206
	v_exp_f32_e32 v207, v207
	v_add_f32_e32 v200, 1.0, v200
	v_add_f32_e32 v201, 1.0, v201
	v_add_f32_e32 v202, 1.0, v202
	v_add_f32_e32 v203, 1.0, v203
	v_add_f32_e32 v204, 1.0, v204
	v_add_f32_e32 v205, 1.0, v205
	v_add_f32_e32 v206, 1.0, v206
	v_add_f32_e32 v207, 1.0, v207
	v_rcp_f32_e32 v200, v200
	v_rcp_f32_e32 v201, v201
	v_rcp_f32_e32 v202, v202
	v_rcp_f32_e32 v203, v203
	v_rcp_f32_e32 v204, v204
	v_rcp_f32_e32 v205, v205
	v_rcp_f32_e32 v206, v206
	v_rcp_f32_e32 v207, v207
	v_mul_f32_e32 v20, v200, v20
	v_mul_f32_e32 v21, v201, v21
	v_mul_f32_e32 v22, v202, v22
	v_mul_f32_e32 v23, v203, v23
	v_mul_f32_e32 v18, v204, v18
	v_mul_f32_e32 v19, v205, v19
	v_mul_f32_e32 v24, v206, v24
	v_mul_f32_e32 v25, v207, v25
.Lsilu_skip_13:
	v_cvt_pk_bf16_f32 v16, v20, v21
	v_cvt_pk_bf16_f32 v17, v22, v23
	v_cvt_pk_bf16_f32 v18, v18, v19
	v_cvt_pk_bf16_f32 v19, v24, v25
	s_cbranch_vccnz .LBB0_547
	v_or3_b32 v20, v34, v53, v154
	v_lshl_or_b32 v20, v20, 6, v162
	v_ashrrev_i32_e32 v21, 31, v20
	v_lshl_add_u64 v[20:21], v[20:21], 3, s[24:25]
	s_mov_b64 s[26:27], 0
	global_store_dwordx2 v[20:21], v[16:17], off
	global_store_dwordx2 v[20:21], v[18:19], off offset:256

; __device__ __forceinline__ unsigned cvt_pk_bf16(float lo, float hi) { unsigned r; asm volatile("v_cvt_pk_bf16_f32 %0, %1, %2" : "=v"(r) : "v"(lo), "v"(hi)); return r; }
;     __device__ __forceinline__ void operator()(const f32x4 (&acc)[2][2][4][2], const Unit& u, int wr, int wc, int fr, int fq) const {
;     ...
;             for (int m = 0; m < 4; ++m) { const int row = row0 + ai * HALF + m * 16;
;                 const float rs = __builtin_amdgcn_rsqf(ssq[row] * (1.0f / 1024.0f) + 1e-6f) * sc;
;                 const int b = row >> 12, tl = row & 4095, tile = tl >> 5, r = tl & 31;
; #pragma unroll
;                 for (int bj = 0; bj < 2; ++bj) { const int cc = (colt & 1023) + bj * HALF + wc * 32 + 8 * fq, h = cc >> 6, d8 = cc & 63, bh = b * 16 + h;
;                     const f32x4 v0 = acc[ai][bj][m][0] * rs, v1 = acc[ai][bj][m][1] * rs;
;                     u32x4 w; w.x = cvt_pk_bf16(v0[0], v0[1]); w.y = cvt_pk_bf16(v0[2], v0[3]); w.z = cvt_pk_bf16(v1[0], v1[1]); w.w = cvt_pk_bf16(v1[2], v1[3]);
;                     if (region < 2) { const int ks = d8 >> 4, hh = (d8 >> 3) & 1;
;                         *(u32x4*)(base + ((size_t)(((bh * 128 + tile) * 4 + ks) * 64 + hh * 32 + r) << 3)) = w;
;                     } else { const int dt = d8 >> 5, g = (d8 >> 3) & 3; bf16_t* p = base + ((size_t)((((bh * 128 + tile) * 2 + dt) * 4 + g) * 64 + r) << 2);
;                         *(unsigned long long*)p = (unsigned long long)w.x | ((unsigned long long)w.y << 32);
;                         *(unsigned long long*)(p + 128) = (unsigned long long)w.z | ((unsigned long long)w.w << 32); } }
.LBB0_549:
	global_load_dword v16, v[146:147], off offset:704
	s_nop 0
	v_add_u32_e32 v17, 0xb0, v144
	v_bfe_u32 v17, v17, 5, 7
	s_and_b64 vcc, exec, s[4:5]
	v_lshl_or_b32 v18, v17, 3, s69
	s_mov_b64 s[26:27], -1
	s_waitcnt vmcnt(0)
	v_fmamk_f32 v16, v16, 0x3a800000, v165
	v_rsq_f32_e32 v16, v16
	s_nop 0
	v_mul_f32_e32 v16, v145, v16
	v_pk_mul_f32 v[20:21], v[10:11], v[16:17] op_sel_hi:[1,0]
	v_pk_mul_f32 v[10:11], v[8:9], v[16:17] op_sel_hi:[1,0]
	v_pk_mul_f32 v[14:15], v[14:15], v[16:17] op_sel_hi:[1,0]
	v_pk_mul_f32 v[12:13], v[12:13], v[16:17] op_sel_hi:[1,0]
	s_nop 0
	s_cmp_eq_u32 s95, 0
	s_cbranch_scc1 .Lsilu_skip_14
	v_mul_f32_e32 v200, 0xbfb8aa3b, v12
	v_mul_f32_e32 v201, 0xbfb8aa3b, v13
	v_mul_f32_e32 v202, 0xbfb8aa3b, v14
	v_mul_f32_e32 v203, 0xbfb8aa3b, v15
	v_mul_f32_e32 v204, 0xbfb8aa3b, v10
	v_mul_f32_e32 v205, 0xbfb8aa3b, v11
	v_mul_f32_e32 v206, 0xbfb8aa3b, v20
	v_mul_f32_e32 v207, 0xbfb8aa3b, v21
	v_exp_f32_e32 v200, v200
	v_exp_f32_e32 v201, v201
	v_exp_f32_e32 v202, v202
	v_exp_f32_e32 v203, v203
	v_exp_f32_e32 v204, v204
	v_exp_f32_e32 v205, v205
	v_exp_f32_e32 v206, v206
	v_exp_f32_e32 v207, v207
	v_add_f32_e32 v200, 1.0, v200
	v_add_f32_e32 v201, 1.0, v201
	v_add_f32_e32 v202, 1.0, v202
	v_add_f32_e32 v203, 1.0, v203
	v_add_f32_e32 v204, 1.0, v204
	v_add_f32_e32 v205, 1.0, v205
	v_add_f32_e32 v206, 1.0, v206
	v_add_f32_e32 v207, 1.0, v207
	v_rcp_f32_e32 v200, v200
	v_rcp_f32_e32 v201, v201
	v_rcp_f32_e32 v202, v202
	v_rcp_f32_e32 v203, v203
	v_rcp_f32_e32 v204, v204
	v_rcp_f32_e32 v205, v205
	v_rcp_f32_e32 v206, v206
	v_rcp_f32_e32 v207, v207
	v_mul_f32_e32 v12, v200, v12
	v_mul_f32_e32 v13, v201, v13
	v_mul_f32_e32 v14, v202, v14
	v_mul_f32_e32 v15, v203, v15
	v_mul_f32_e32 v10, v204, v10
	v_mul_f32_e32 v11, v205, v11
	v_mul_f32_e32 v20, v206, v20
	v_mul_f32_e32 v21, v207, v21
.Lsilu_skip_14:
	v_cvt_pk_bf16_f32 v8, v12, v13
	v_cvt_pk_bf16_f32 v9, v14, v15
	v_cvt_pk_bf16_f32 v10, v10, v11
	v_cvt_pk_bf16_f32 v11, v20, v21
	s_cbranch_vccnz .LBB0_551
	v_or3_b32 v12, v18, v61, v154
	v_lshl_or_b32 v12, v12, 6, v158
	v_ashrrev_i32_e32 v13, 31, v12
	v_lshl_add_u64 v[12:13], v[12:13], 3, s[24:25]
	s_mov_b64 s[26:27], 0
	global_store_dwordx2 v[12:13], v[8:9], off
	global_store_dwordx2 v[12:13], v[10:11], off offset:256

; __device__ __forceinline__ unsigned cvt_pk_bf16(float lo, float hi) { unsigned r; asm volatile("v_cvt_pk_bf16_f32 %0, %1, %2" : "=v"(r) : "v"(lo), "v"(hi)); return r; }
;     __device__ __forceinline__ void operator()(const f32x4 (&acc)[2][2][4][2], const Unit& u, int wr, int wc, int fr, int fq) const {
;     ...
;             for (int m = 0; m < 4; ++m) { const int row = row0 + ai * HALF + m * 16;
;                 const float rs = __builtin_amdgcn_rsqf(ssq[row] * (1.0f / 1024.0f) + 1e-6f) * sc;
;                 const int b = row >> 12, tl = row & 4095, tile = tl >> 5, r = tl & 31;
; #pragma unroll
;                 for (int bj = 0; bj < 2; ++bj) { const int cc = (colt & 1023) + bj * HALF + wc * 32 + 8 * fq, h = cc >> 6, d8 = cc & 63, bh = b * 16 + h;
;                     const f32x4 v0 = acc[ai][bj][m][0] * rs, v1 = acc[ai][bj][m][1] * rs;
;                     u32x4 w; w.x = cvt_pk_bf16(v0[0], v0[1]); w.y = cvt_pk_bf16(v0[2], v0[3]); w.z = cvt_pk_bf16(v1[0], v1[1]); w.w = cvt_pk_bf16(v1[2], v1[3]);
;                     if (region < 2) { const int ks = d8 >> 4, hh = (d8 >> 3) & 1;
;                         *(u32x4*)(base + ((size_t)(((bh * 128 + tile) * 4 + ks) * 64 + hh * 32 + r) << 3)) = w;
;                     } else { const int dt = d8 >> 5, g = (d8 >> 3) & 3; bf16_t* p = base + ((size_t)((((bh * 128 + tile) * 2 + dt) * 4 + g) * 64 + r) << 2);
;                         *(unsigned long long*)p = (unsigned long long)w.x | ((unsigned long long)w.y << 32);
;                         *(unsigned long long*)(p + 128) = (unsigned long long)w.z | ((unsigned long long)w.w << 32); } }
.LBB0_553:
	v_mov_b32_e32 v17, v16
	s_nop 0
	v_mov_b32_e32 v8, v16
	v_mov_b32_e32 v9, v16
	v_pk_mul_f32 v[6:7], v[6:7], v[8:9]
	v_pk_mul_f32 v[8:9], v[2:3], v[8:9]
	v_pk_mul_f32 v[2:3], v[0:1], v[16:17]
	s_and_b64 vcc, exec, s[4:5]
	s_mov_b64 s[4:5], -1
	v_pk_mul_f32 v[4:5], v[4:5], v[16:17]
	s_nop 0
	s_cmp_eq_u32 s95, 0
	s_cbranch_scc1 .Lsilu_skip_15
	v_mul_f32_e32 v200, 0xbfb8aa3b, v4
	v_mul_f32_e32 v201, 0xbfb8aa3b, v5
	v_mul_f32_e32 v202, 0xbfb8aa3b, v6
	v_mul_f32_e32 v203, 0xbfb8aa3b, v7
	v_mul_f32_e32 v204, 0xbfb8aa3b, v2
	v_mul_f32_e32 v205, 0xbfb8aa3b, v3
	v_mul_f32_e32 v206, 0xbfb8aa3b, v8
	v_mul_f32_e32 v207, 0xbfb8aa3b, v9
	v_exp_f32_e32 v200, v200
	v_exp_f32_e32 v201, v201
	v_exp_f32_e32 v202, v202
	v_exp_f32_e32 v203, v203
	v_exp_f32_e32 v204, v204
	v_exp_f32_e32 v205, v205
	v_exp_f32_e32 v206, v206
	v_exp_f32_e32 v207, v207
	v_add_f32_e32 v200, 1.0, v200
	v_add_f32_e32 v201, 1.0, v201
	v_add_f32_e32 v202, 1.0, v202
	v_add_f32_e32 v203, 1.0, v203
	v_add_f32_e32 v204, 1.0, v204
	v_add_f32_e32 v205, 1.0, v205
	v_add_f32_e32 v206, 1.0, v206
	v_add_f32_e32 v207, 1.0, v207
	v_rcp_f32_e32 v200, v200
	v_rcp_f32_e32 v201, v201
	v_rcp_f32_e32 v202, v202
	v_rcp_f32_e32 v203, v203
	v_rcp_f32_e32 v204, v204
	v_rcp_f32_e32 v205, v205
	v_rcp_f32_e32 v206, v206
	v_rcp_f32_e32 v207, v207
	v_mul_f32_e32 v4, v200, v4
	v_mul_f32_e32 v5, v201, v5
	v_mul_f32_e32 v6, v202, v6
	v_mul_f32_e32 v7, v203, v7
	v_mul_f32_e32 v2, v204, v2
	v_mul_f32_e32 v3, v205, v3
	v_mul_f32_e32 v8, v206, v8
	v_mul_f32_e32 v9, v207, v9
.Lsilu_skip_15:
	v_cvt_pk_bf16_f32 v0, v4, v5
	v_cvt_pk_bf16_f32 v1, v6, v7
	v_cvt_pk_bf16_f32 v2, v2, v3
	v_cvt_pk_bf16_f32 v3, v8, v9
	s_cbranch_vccnz .LBB0_555
	v_or3_b32 v4, v18, v53, v154
	v_lshl_or_b32 v4, v4, 6, v158
	v_ashrrev_i32_e32 v5, 31, v4
	v_lshl_add_u64 v[4:5], v[4:5], 3, s[24:25]
	s_mov_b64 s[4:5], 0
	global_store_dwordx2 v[4:5], v[0:1], off
	global_store_dwordx2 v[4:5], v[2:3], off offset:256

; __device__ __forceinline__ unsigned pk2(float lo, float hi) { f32x2_t v = {lo, hi}; bf16x2_t b = __builtin_convertvector(v, bf16x2_t); return __builtin_bit_cast(unsigned, b); }
; __device__ __forceinline__ float bflo(unsigned u) { return __uint_as_float(u << 16); }
; __device__ __forceinline__ float bfhi(unsigned u) { return __uint_as_float(u & 0xffff0000u); }
; __device__ __forceinline__ float sigmoid_(float x) { return rcpf_(1.0f + ex2(-LOG2E * x)); }
; __device__ __forceinline__ void attn_phase(const Ptrs& P, int gw, int NGW, int lane) {
;     ...
; #pragma unroll
;         for (int dt = 0; dt < 2; ++dt)
; #pragma unroll
;             for (int g = 0; g < 4; g += 2) { v2u pk[2];
; #pragma unroll
;                 for (int e = 0; e < 2; ++e) { const v2u graw = gq_[dt * 4 + g + e]; const int i0 = 4 * (g + e);
;                     const float g0 = bflo(graw.x), g1 = bfhi(graw.x), g2 = bflo(graw.y), g3 = bfhi(graw.y);
;                     const float v0 = dt ? o1[i0] : o0[i0], v1 = dt ? o1[i0 + 1] : o0[i0 + 1], v2 = dt ? o1[i0 + 2] : o0[i0 + 2], v3 = dt ? o1[i0 + 3] : o0[i0 + 3];
;                     float w0 = v0 * (g0 * sigmoid_(g0)), w1 = v1 * (g1 * sigmoid_(g1)), w2 = v2 * (g2 * sigmoid_(g2)), w3 = v3 * (g3 * sigmoid_(g3));
;                     asm("" : "+v"(w0)); asm("" : "+v"(w1)); asm("" : "+v"(w2)); asm("" : "+v"(w3));
;                     pk[e].x = pk2(w0, w1); pk[e].y = pk2(w2, w3); }
;                 const auto rx = __builtin_amdgcn_permlane32_swap(pk[0].x, pk[1].x, false, false), ry = __builtin_amdgcn_permlane32_swap(pk[0].y, pk[1].y, false, false);
;                 const v4u o = {rx[0], ry[0], rx[1], ry[1]};
;                 *(v4u*)(op + dt * 32 + 8 * g) = o; }
.Lp6_epi_compute:
	v_lshlrev_b32_e32 v240, 16, v187
	v_and_b32_e32 v241, 0xffff0000, v187
	v_lshlrev_b32_e32 v242, 16, v188
	v_and_b32_e32 v243, 0xffff0000, v188
	v_mul_f32_e32 v240, v240, v0
	v_mul_f32_e32 v241, v241, v1
	v_mul_f32_e32 v242, v242, v2
	v_mul_f32_e32 v243, v243, v3
	v_cvt_pk_bf16_f32 v248, v240, v241
	v_cvt_pk_bf16_f32 v249, v242, v243
	v_lshlrev_b32_e32 v240, 16, v189
	v_and_b32_e32 v241, 0xffff0000, v189
	v_lshlrev_b32_e32 v242, 16, v190
	v_and_b32_e32 v243, 0xffff0000, v190
	v_mul_f32_e32 v240, v240, v4
	v_mul_f32_e32 v241, v241, v5
	v_mul_f32_e32 v242, v242, v6
	v_mul_f32_e32 v243, v243, v7
	v_cvt_pk_bf16_f32 v250, v240, v241
	v_cvt_pk_bf16_f32 v251, v242, v243
	s_nop 1
	v_permlane32_swap_b32_e32 v248, v250
	v_permlane32_swap_b32_e32 v249, v251
	global_store_dwordx4 v239, v[248:251], s[42:43]
	s_nop 1
	v_lshlrev_b32_e32 v240, 16, v191
	v_and_b32_e32 v241, 0xffff0000, v191
	v_lshlrev_b32_e32 v242, 16, v192
	v_and_b32_e32 v243, 0xffff0000, v192
	v_mul_f32_e32 v240, v240, v8
	v_mul_f32_e32 v241, v241, v9
	v_mul_f32_e32 v242, v242, v10
	v_mul_f32_e32 v243, v243, v11
	v_cvt_pk_bf16_f32 v248, v240, v241
	v_cvt_pk_bf16_f32 v249, v242, v243
	v_lshlrev_b32_e32 v240, 16, v193
	v_and_b32_e32 v241, 0xffff0000, v193
	v_lshlrev_b32_e32 v242, 16, v194
	v_and_b32_e32 v243, 0xffff0000, v194
	v_mul_f32_e32 v240, v240, v12
	v_mul_f32_e32 v241, v241, v13
	v_mul_f32_e32 v242, v242, v14
	v_mul_f32_e32 v243, v243, v15
	v_cvt_pk_bf16_f32 v250, v240, v241
	v_cvt_pk_bf16_f32 v251, v242, v243
	s_nop 1
	v_permlane32_swap_b32_e32 v248, v250
	v_permlane32_swap_b32_e32 v249, v251
	global_store_dwordx4 v239, v[248:251], s[42:43] offset:32
	s_nop 1
	v_lshlrev_b32_e32 v240, 16, v195
	v_and_b32_e32 v241, 0xffff0000, v195
	v_lshlrev_b32_e32 v242, 16, v196
	v_and_b32_e32 v243, 0xffff0000, v196
	v_mul_f32_e32 v240, v240, v16
	v_mul_f32_e32 v241, v241, v17
	v_mul_f32_e32 v242, v242, v18
	v_mul_f32_e32 v243, v243, v19
	v_cvt_pk_bf16_f32 v248, v240, v241
	v_cvt_pk_bf16_f32 v249, v242, v243
	v_lshlrev_b32_e32 v240, 16, v197
	v_and_b32_e32 v241, 0xffff0000, v197
	v_lshlrev_b32_e32 v242, 16, v198
	v_and_b32_e32 v243, 0xffff0000, v198
	v_mul_f32_e32 v240, v240, v20
	v_mul_f32_e32 v241, v241, v21
	v_mul_f32_e32 v242, v242, v22
	v_mul_f32_e32 v243, v243, v23
	v_cvt_pk_bf16_f32 v250, v240, v241
	v_cvt_pk_bf16_f32 v251, v242, v243
	s_nop 1
	v_permlane32_swap_b32_e32 v248, v250
	v_permlane32_swap_b32_e32 v249, v251
	global_store_dwordx4 v239, v[248:251], s[42:43] offset:64
	s_nop 1
	v_lshlrev_b32_e32 v240, 16, v199
	v_and_b32_e32 v241, 0xffff0000, v199
	v_lshlrev_b32_e32 v242, 16, v200
	v_and_b32_e32 v243, 0xffff0000, v200
	v_mul_f32_e32 v240, v240, v24
	v_mul_f32_e32 v241, v241, v25
	v_mul_f32_e32 v242, v242, v26
	v_mul_f32_e32 v243, v243, v27
	v_cvt_pk_bf16_f32 v248, v240, v241
	v_cvt_pk_bf16_f32 v249, v242, v243
	v_lshlrev_b32_e32 v240, 16, v201
	v_and_b32_e32 v241, 0xffff0000, v201
	v_lshlrev_b32_e32 v242, 16, v202
	v_and_b32_e32 v243, 0xffff0000, v202
	v_mul_f32_e32 v240, v240, v28
	v_mul_f32_e32 v241, v241, v29
	v_mul_f32_e32 v242, v242, v30
	v_mul_f32_e32 v243, v243, v31
	v_cvt_pk_bf16_f32 v250, v240, v241
	v_cvt_pk_bf16_f32 v251, v242, v243
	s_nop 1
	v_permlane32_swap_b32_e32 v248, v250
	v_permlane32_swap_b32_e32 v249, v251
	global_store_dwordx4 v239, v[248:251], s[42:43] offset:96
	s_nop 1
	s_cmp_lg_u32 s82, 0
	s_cbranch_scc1 .Lp6_unit

; __global__ void __launch_bounds__(NT, 2) trunk_fwd(Args args) {
;     extern __shared__ __attribute__((aligned(16))) unsigned char lds_raw[];
	.amdhsa_kernel _Z9trunk_fwd4Args
		.amdhsa_group_segment_fixed_size 0
		.amdhsa_private_segment_fixed_size 0
		.amdhsa_kernarg_size 384
		.amdhsa_user_sgpr_count 2
		.amdhsa_user_sgpr_dispatch_ptr 0
		.amdhsa_user_sgpr_queue_ptr 0
		.amdhsa_user_sgpr_kernarg_segment_ptr 1
		.amdhsa_user_sgpr_dispatch_id 0
		.amdhsa_user_sgpr_kernarg_preload_length 0
		.amdhsa_user_sgpr_kernarg_preload_offset 0
		.amdhsa_user_sgpr_private_segment_size 0
		.amdhsa_uses_dynamic_stack 0
		.amdhsa_enable_private_segment 0
		.amdhsa_system_sgpr_workgroup_id_x 1
		.amdhsa_system_sgpr_workgroup_id_y 0
		.amdhsa_system_sgpr_workgroup_id_z 0
		.amdhsa_system_sgpr_workgroup_info 0
		.amdhsa_system_vgpr_workitem_id 2
		.amdhsa_next_free_vgpr 252
		.amdhsa_next_free_sgpr 96
		.amdhsa_accum_offset 252
		.amdhsa_reserve_vcc 1
		.amdhsa_float_round_mode_32 0
		.amdhsa_float_round_mode_16_64 0
		.amdhsa_float_denorm_mode_32 3
		.amdhsa_float_denorm_mode_16_64 3
		.amdhsa_dx10_clamp 1
		.amdhsa_ieee_mode 1
		.amdhsa_fp16_overflow 0
		.amdhsa_tg_split 0
		.amdhsa_exception_fp_ieee_invalid_op 0
		.amdhsa_exception_fp_denorm_src 0
		.amdhsa_exception_fp_ieee_div_zero 0
		.amdhsa_exception_fp_ieee_overflow 0
		.amdhsa_exception_fp_ieee_underflow 0
		.amdhsa_exception_fp_ieee_inexact 0
		.amdhsa_exception_int_div_zero 0
	.end_amdhsa_kernel

; __global__ void __launch_bounds__(NT, 2) trunk_fwd(Args args) {
;     extern __shared__ __attribute__((aligned(16))) unsigned char lds_raw[];
amdhsa.kernels:
  - .agpr_count:     0
    .args:
      - .offset:         0
        .size:           128
        .value_kind:     by_value
      - .offset:         128
        .size:           4
        .value_kind:     hidden_block_count_x
      - .offset:         132
        .size:           4
        .value_kind:     hidden_block_count_y
      - .offset:         136
        .size:           4
        .value_kind:     hidden_block_count_z
      - .offset:         140
        .size:           2
        .value_kind:     hidden_group_size_x
      - .offset:         142
        .size:           2
        .value_kind:     hidden_group_size_y
      - .offset:         144
        .size:           2
        .value_kind:     hidden_group_size_z
      - .offset:         146
        .size:           2
        .value_kind:     hidden_remainder_x
      - .offset:         148
        .size:           2
        .value_kind:     hidden_remainder_y
      - .offset:         150
        .size:           2
        .value_kind:     hidden_remainder_z
      - .offset:         168
        .size:           8
        .value_kind:     hidden_global_offset_x
      - .offset:         176
        .size:           8
        .value_kind:     hidden_global_offset_y
      - .offset:         184
        .size:           8
        .value_kind:     hidden_global_offset_z
      - .offset:         192
        .size:           2
        .value_kind:     hidden_grid_dims
      - .offset:         216
        .size:           8
        .value_kind:     hidden_multigrid_sync_arg
      - .offset:         248
        .size:           4
        .value_kind:     hidden_dynamic_lds_size
    .group_segment_fixed_size: 0
    .kernarg_segment_align: 8
    .kernarg_segment_size: 384
    .language:       OpenCL C
    .language_version:
      - 2
      - 0
    .max_flat_workgroup_size: 512
    .name:           _Z9trunk_fwd4Args
    .private_segment_fixed_size: 0
    .sgpr_count:     102
    .sgpr_spill_count: 0
    .symbol:         _Z9trunk_fwd4Args.kd
    .uniform_work_group_size: 1
    .uses_dynamic_stack: false
    .vgpr_count:     252
    .vgpr_spill_count: 0
    .wavefront_size: 64
